# weight-conversion f32 loads and mla_mid reads marked nt (on top of nt row-pass loads, write-through stores, MLA prio)
# speedup vs baseline: 1.0152x; 1.0080x over previous
; #define LAS __attribute__((address_space(3)))
; __device__ __forceinline__ void wt_item(const float* __restrict__ W, int ldw, int K, int src_c0, bf16_t* __restrict__ WT, int dst_r0, int k0, LAS float* scr, int lane, int Ndst) {
; #pragma unroll 32
;     for (int i = 0; i < 32; ++i) { const int kk = 2 * i + (lane >> 5); scr[kk * 33 + (lane & 31)] = (src_c0 >= 0) ? W[(size_t)(k0 + kk) * ldw + src_c0 + (lane & 31)] : 0.f; }
; __device__ __forceinline__ void conv_plain(const float* W, int K, int N, bf16_t* WT, LAS float* scr, int gw, int NGW, int lane) {
;     const int nblk = N / 32, items = (K / 64) * nblk;
;     for (int it = gw; it < items; it += NGW) { const int kb = it / nblk, nb = it % nblk; wt_item(W, N, K, nb * 32, WT, nb * 32, kb * 64, scr, lane, N); }
.LBB0_15:
	s_ashr_i32 s6, s4, 8
	s_lshl_b32 s4, s6, 13
	s_sub_i32 s4, s12, s4
	s_lshl_b32 s7, s6, 6
	v_lshl_add_u64 v[10:11], s[4:5], 2, v[6:7]
	v_mov_b32_e32 v5, 0
	s_andn2_b64 vcc, exec, s[0:1]
	v_mov_b32_e32 v58, 0
	v_mov_b32_e32 v59, 0
	v_mov_b32_e32 v60, 0
	s_cbranch_vccnz .LBB0_17
	v_or_b32_e32 v58, s7, v13
	v_ashrrev_i32_e32 v59, 31, v58
	v_lshlrev_b64 v[58:59], 15, v[58:59]
	v_lshl_add_u64 v[62:63], v[10:11], 0, v[58:59]
	v_or_b32_e32 v58, s7, v14
	v_ashrrev_i32_e32 v59, 31, v58
	v_lshlrev_b64 v[58:59], 15, v[58:59]
	v_lshl_add_u64 v[64:65], v[10:11], 0, v[58:59]
	v_or_b32_e32 v58, s7, v15
	v_ashrrev_i32_e32 v59, 31, v58
	v_lshlrev_b64 v[58:59], 15, v[58:59]
	v_lshl_add_u64 v[66:67], v[10:11], 0, v[58:59]
	v_or_b32_e32 v58, s7, v16
	v_ashrrev_i32_e32 v59, 31, v58
	v_lshlrev_b64 v[58:59], 15, v[58:59]
	v_lshl_add_u64 v[68:69], v[10:11], 0, v[58:59]
	v_or_b32_e32 v58, s7, v17
	v_ashrrev_i32_e32 v59, 31, v58
	v_lshlrev_b64 v[58:59], 15, v[58:59]
	v_lshl_add_u64 v[70:71], v[10:11], 0, v[58:59]
	v_or_b32_e32 v58, s7, v18
	v_ashrrev_i32_e32 v59, 31, v58
	v_lshlrev_b64 v[58:59], 15, v[58:59]
	v_lshl_add_u64 v[72:73], v[10:11], 0, v[58:59]
	v_or_b32_e32 v58, s7, v19
	v_ashrrev_i32_e32 v59, 31, v58
	v_lshlrev_b64 v[58:59], 15, v[58:59]
	v_lshl_add_u64 v[74:75], v[10:11], 0, v[58:59]
	v_or_b32_e32 v58, s7, v20
	v_ashrrev_i32_e32 v59, 31, v58
	v_lshlrev_b64 v[58:59], 15, v[58:59]
	v_lshl_add_u64 v[76:77], v[10:11], 0, v[58:59]
	global_load_dword v61, v[62:63], off nt
	global_load_dword v78, v[64:65], off nt
	global_load_dword v79, v[66:67], off nt
	global_load_dword v80, v[68:69], off nt
	global_load_dword v5, v[70:71], off nt
	global_load_dword v58, v[72:73], off nt
	global_load_dword v59, v[74:75], off nt
	global_load_dword v60, v[76:77], off nt
	s_waitcnt vmcnt(6)
	ds_write2_b32 v50, v61, v78 offset1:66
	s_waitcnt vmcnt(4)
	ds_write2_b32 v50, v79, v80 offset0:132 offset1:198

; #define LAS __attribute__((address_space(3)))
; __device__ __forceinline__ void wt_item(const float* __restrict__ W, int ldw, int K, int src_c0, bf16_t* __restrict__ WT, int dst_r0, int k0, LAS float* scr, int lane, int Ndst) {
; #pragma unroll 32
;     for (int i = 0; i < 32; ++i) { const int kk = 2 * i + (lane >> 5); scr[kk * 33 + (lane & 31)] = (src_c0 >= 0) ? W[(size_t)(k0 + kk) * ldw + src_c0 + (lane & 31)] : 0.f; }
.LBB0_19:
	v_mov_b32_e32 v5, 0
	s_andn2_b64 vcc, exec, s[0:1]
	v_mov_b32_e32 v58, 0
	v_mov_b32_e32 v59, 0
	v_mov_b32_e32 v60, 0
	s_cbranch_vccnz .LBB0_21
	v_or_b32_e32 v58, s7, v21
	v_ashrrev_i32_e32 v59, 31, v58
	v_lshlrev_b64 v[58:59], 15, v[58:59]
	v_lshl_add_u64 v[62:63], v[10:11], 0, v[58:59]
	v_or_b32_e32 v58, s7, v22
	v_ashrrev_i32_e32 v59, 31, v58
	v_lshlrev_b64 v[58:59], 15, v[58:59]
	v_lshl_add_u64 v[64:65], v[10:11], 0, v[58:59]
	v_or_b32_e32 v58, s7, v23
	v_ashrrev_i32_e32 v59, 31, v58
	v_lshlrev_b64 v[58:59], 15, v[58:59]
	v_lshl_add_u64 v[66:67], v[10:11], 0, v[58:59]
	v_or_b32_e32 v58, s7, v24
	v_ashrrev_i32_e32 v59, 31, v58
	v_lshlrev_b64 v[58:59], 15, v[58:59]
	v_lshl_add_u64 v[68:69], v[10:11], 0, v[58:59]
	v_or_b32_e32 v58, s7, v25
	v_ashrrev_i32_e32 v59, 31, v58
	v_lshlrev_b64 v[58:59], 15, v[58:59]
	v_lshl_add_u64 v[70:71], v[10:11], 0, v[58:59]
	v_or_b32_e32 v58, s7, v26
	v_ashrrev_i32_e32 v59, 31, v58
	v_lshlrev_b64 v[58:59], 15, v[58:59]
	v_lshl_add_u64 v[72:73], v[10:11], 0, v[58:59]
	v_or_b32_e32 v58, s7, v27
	v_ashrrev_i32_e32 v59, 31, v58
	v_lshlrev_b64 v[58:59], 15, v[58:59]
	v_lshl_add_u64 v[74:75], v[10:11], 0, v[58:59]
	v_or_b32_e32 v58, s7, v28
	v_ashrrev_i32_e32 v59, 31, v58
	v_lshlrev_b64 v[58:59], 15, v[58:59]
	v_lshl_add_u64 v[76:77], v[10:11], 0, v[58:59]
	global_load_dword v61, v[62:63], off nt
	global_load_dword v78, v[64:65], off nt
	global_load_dword v79, v[66:67], off nt
	global_load_dword v80, v[68:69], off nt
	global_load_dword v5, v[70:71], off nt
	global_load_dword v58, v[72:73], off nt
	global_load_dword v59, v[74:75], off nt
	global_load_dword v60, v[76:77], off nt
	v_add_u32_e32 v62, v56, v52
	s_waitcnt vmcnt(6)
	ds_write2_b32 v62, v61, v78 offset1:66
	s_waitcnt vmcnt(4)
	ds_write2_b32 v62, v79, v80 offset0:132 offset1:198

; #define LAS __attribute__((address_space(3)))
; __device__ __forceinline__ void wt_item(const float* __restrict__ W, int ldw, int K, int src_c0, bf16_t* __restrict__ WT, int dst_r0, int k0, LAS float* scr, int lane, int Ndst) {
; #pragma unroll 32
;     for (int i = 0; i < 32; ++i) { const int kk = 2 * i + (lane >> 5); scr[kk * 33 + (lane & 31)] = (src_c0 >= 0) ? W[(size_t)(k0 + kk) * ldw + src_c0 + (lane & 31)] : 0.f; }
.LBB0_23:
	v_mov_b32_e32 v5, 0
	s_andn2_b64 vcc, exec, s[0:1]
	v_mov_b32_e32 v58, 0
	v_mov_b32_e32 v59, 0
	v_mov_b32_e32 v60, 0
	s_cbranch_vccnz .LBB0_25
	v_or_b32_e32 v58, s7, v29
	v_ashrrev_i32_e32 v59, 31, v58
	v_lshlrev_b64 v[58:59], 15, v[58:59]
	v_lshl_add_u64 v[62:63], v[10:11], 0, v[58:59]
	v_or_b32_e32 v58, s7, v30
	v_ashrrev_i32_e32 v59, 31, v58
	v_lshlrev_b64 v[58:59], 15, v[58:59]
	v_lshl_add_u64 v[64:65], v[10:11], 0, v[58:59]
	v_or_b32_e32 v58, s7, v31
	v_ashrrev_i32_e32 v59, 31, v58
	v_lshlrev_b64 v[58:59], 15, v[58:59]
	v_lshl_add_u64 v[66:67], v[10:11], 0, v[58:59]
	v_or_b32_e32 v58, s7, v32
	v_ashrrev_i32_e32 v59, 31, v58
	v_lshlrev_b64 v[58:59], 15, v[58:59]
	v_lshl_add_u64 v[68:69], v[10:11], 0, v[58:59]
	v_or_b32_e32 v58, s7, v33
	v_ashrrev_i32_e32 v59, 31, v58
	v_lshlrev_b64 v[58:59], 15, v[58:59]
	v_lshl_add_u64 v[70:71], v[10:11], 0, v[58:59]
	v_or_b32_e32 v58, s7, v34
	v_ashrrev_i32_e32 v59, 31, v58
	v_lshlrev_b64 v[58:59], 15, v[58:59]
	v_lshl_add_u64 v[72:73], v[10:11], 0, v[58:59]
	v_or_b32_e32 v58, s7, v35
	v_ashrrev_i32_e32 v59, 31, v58
	v_lshlrev_b64 v[58:59], 15, v[58:59]
	v_lshl_add_u64 v[74:75], v[10:11], 0, v[58:59]
	v_or_b32_e32 v58, s7, v36
	v_ashrrev_i32_e32 v59, 31, v58
	v_lshlrev_b64 v[58:59], 15, v[58:59]
	v_lshl_add_u64 v[76:77], v[10:11], 0, v[58:59]
	global_load_dword v61, v[62:63], off nt
	global_load_dword v78, v[64:65], off nt
	global_load_dword v79, v[66:67], off nt
	global_load_dword v80, v[68:69], off nt
	global_load_dword v5, v[70:71], off nt
	global_load_dword v58, v[72:73], off nt
	global_load_dword v59, v[74:75], off nt
	global_load_dword v60, v[76:77], off nt
	v_add_u32_e32 v62, v56, v54
	s_waitcnt vmcnt(6)
	ds_write2_b32 v62, v61, v78 offset1:66
	s_waitcnt vmcnt(4)
	ds_write2_b32 v62, v79, v80 offset0:132 offset1:198

; #define LAS __attribute__((address_space(3)))
; __device__ __forceinline__ void wt_item(const float* __restrict__ W, int ldw, int K, int src_c0, bf16_t* __restrict__ WT, int dst_r0, int k0, LAS float* scr, int lane, int Ndst) {
; #pragma unroll 32
;     for (int i = 0; i < 32; ++i) { const int kk = 2 * i + (lane >> 5); scr[kk * 33 + (lane & 31)] = (src_c0 >= 0) ? W[(size_t)(k0 + kk) * ldw + src_c0 + (lane & 31)] : 0.f; }
.LBB0_27:
	v_mov_b32_e32 v5, 0
	s_andn2_b64 vcc, exec, s[0:1]
	v_mov_b32_e32 v58, 0
	v_mov_b32_e32 v59, 0
	v_mov_b32_e32 v60, 0
	s_cbranch_vccnz .LBB0_12
	v_or_b32_e32 v58, s7, v37
	v_ashrrev_i32_e32 v59, 31, v58
	v_lshlrev_b64 v[58:59], 15, v[58:59]
	v_lshl_add_u64 v[62:63], v[10:11], 0, v[58:59]
	v_or_b32_e32 v58, s7, v38
	v_ashrrev_i32_e32 v59, 31, v58
	v_lshlrev_b64 v[58:59], 15, v[58:59]
	v_lshl_add_u64 v[64:65], v[10:11], 0, v[58:59]
	v_or_b32_e32 v58, s7, v39
	v_ashrrev_i32_e32 v59, 31, v58
	v_lshlrev_b64 v[58:59], 15, v[58:59]
	v_lshl_add_u64 v[66:67], v[10:11], 0, v[58:59]
	v_or_b32_e32 v58, s7, v40
	v_ashrrev_i32_e32 v59, 31, v58
	v_lshlrev_b64 v[58:59], 15, v[58:59]
	v_lshl_add_u64 v[68:69], v[10:11], 0, v[58:59]
	v_or_b32_e32 v58, s7, v41
	v_ashrrev_i32_e32 v59, 31, v58
	v_lshlrev_b64 v[58:59], 15, v[58:59]
	v_lshl_add_u64 v[70:71], v[10:11], 0, v[58:59]
	v_or_b32_e32 v58, s7, v42
	v_ashrrev_i32_e32 v59, 31, v58
	v_lshlrev_b64 v[58:59], 15, v[58:59]
	v_lshl_add_u64 v[72:73], v[10:11], 0, v[58:59]
	v_or_b32_e32 v58, s7, v43
	v_ashrrev_i32_e32 v59, 31, v58
	v_lshlrev_b64 v[58:59], 15, v[58:59]
	v_lshl_add_u64 v[74:75], v[10:11], 0, v[58:59]
	v_or_b32_e32 v58, s7, v44
	v_ashrrev_i32_e32 v59, 31, v58
	v_lshlrev_b64 v[58:59], 15, v[58:59]
	v_lshl_add_u64 v[10:11], v[10:11], 0, v[58:59]
	global_load_dword v61, v[62:63], off nt
	global_load_dword v76, v[64:65], off nt
	global_load_dword v77, v[66:67], off nt
	global_load_dword v78, v[68:69], off nt
	global_load_dword v5, v[70:71], off nt
	global_load_dword v58, v[72:73], off nt
	global_load_dword v59, v[74:75], off nt
	global_load_dword v60, v[10:11], off nt
	v_add_u32_e32 v10, v56, v57
	s_waitcnt vmcnt(6)
	ds_write2_b32 v10, v61, v76 offset1:66
	s_waitcnt vmcnt(4)
	ds_write2_b32 v10, v77, v78 offset0:132 offset1:198
	s_branch .LBB0_12

; #define LAS __attribute__((address_space(3)))
; __device__ __forceinline__ void wt_item(const float* __restrict__ W, int ldw, int K, int src_c0, bf16_t* __restrict__ WT, int dst_r0, int k0, LAS float* scr, int lane, int Ndst) {
; #pragma unroll 32
;     for (int i = 0; i < 32; ++i) { const int kk = 2 * i + (lane >> 5); scr[kk * 33 + (lane & 31)] = (src_c0 >= 0) ? W[(size_t)(k0 + kk) * ldw + src_c0 + (lane & 31)] : 0.f; }
; __device__ __forceinline__ void conv_plain(const float* W, int K, int N, bf16_t* WT, LAS float* scr, int gw, int NGW, int lane) {
;     const int nblk = N / 32, items = (K / 64) * nblk;
;     for (int it = gw; it < items; it += NGW) { const int kb = it / nblk, nb = it % nblk; wt_item(W, N, K, nb * 32, WT, nb * 32, kb * 64, scr, lane, N); }
.LBB0_34:
	s_ashr_i32 s12, s4, 6
	s_lshl_b32 s4, s12, 11
	s_sub_i32 s4, s16, s4
	v_lshl_add_u64 v[10:11], s[4:5], 2, v[6:7]
	v_mov_b32_e32 v5, 0
	s_andn2_b64 vcc, exec, s[0:1]
	v_mov_b32_e32 v58, 0
	v_mov_b32_e32 v59, 0
	v_mov_b32_e32 v60, 0
	s_cbranch_vccnz .LBB0_36
	v_or_b32_e32 v58, s13, v13
	v_ashrrev_i32_e32 v59, 31, v58
	v_lshlrev_b64 v[58:59], 13, v[58:59]
	v_lshl_add_u64 v[62:63], v[10:11], 0, v[58:59]
	v_or_b32_e32 v58, s13, v14
	v_ashrrev_i32_e32 v59, 31, v58
	v_lshlrev_b64 v[58:59], 13, v[58:59]
	v_lshl_add_u64 v[64:65], v[10:11], 0, v[58:59]
	v_or_b32_e32 v58, s13, v15
	v_ashrrev_i32_e32 v59, 31, v58
	v_lshlrev_b64 v[58:59], 13, v[58:59]
	v_lshl_add_u64 v[66:67], v[10:11], 0, v[58:59]
	v_or_b32_e32 v58, s13, v16
	v_ashrrev_i32_e32 v59, 31, v58
	v_lshlrev_b64 v[58:59], 13, v[58:59]
	v_lshl_add_u64 v[68:69], v[10:11], 0, v[58:59]
	v_or_b32_e32 v58, s13, v17
	v_ashrrev_i32_e32 v59, 31, v58
	v_lshlrev_b64 v[58:59], 13, v[58:59]
	v_lshl_add_u64 v[70:71], v[10:11], 0, v[58:59]
	v_or_b32_e32 v58, s13, v18
	v_ashrrev_i32_e32 v59, 31, v58
	v_lshlrev_b64 v[58:59], 13, v[58:59]
	v_lshl_add_u64 v[72:73], v[10:11], 0, v[58:59]
	v_or_b32_e32 v58, s13, v19
	v_ashrrev_i32_e32 v59, 31, v58
	v_lshlrev_b64 v[58:59], 13, v[58:59]
	v_lshl_add_u64 v[74:75], v[10:11], 0, v[58:59]
	v_or_b32_e32 v58, s13, v20
	v_ashrrev_i32_e32 v59, 31, v58
	v_lshlrev_b64 v[58:59], 13, v[58:59]
	v_lshl_add_u64 v[76:77], v[10:11], 0, v[58:59]
	global_load_dword v61, v[62:63], off nt
	global_load_dword v78, v[64:65], off nt
	global_load_dword v79, v[66:67], off nt
	global_load_dword v80, v[68:69], off nt
	global_load_dword v5, v[70:71], off nt
	global_load_dword v58, v[72:73], off nt
	global_load_dword v59, v[74:75], off nt
	global_load_dword v60, v[76:77], off nt
	s_waitcnt vmcnt(6)
	ds_write2_b32 v50, v61, v78 offset1:66
	s_waitcnt vmcnt(4)
	ds_write2_b32 v50, v79, v80 offset0:132 offset1:198

; #define LAS __attribute__((address_space(3)))
; __device__ __forceinline__ void wt_item(const float* __restrict__ W, int ldw, int K, int src_c0, bf16_t* __restrict__ WT, int dst_r0, int k0, LAS float* scr, int lane, int Ndst) {
; #pragma unroll 32
;     for (int i = 0; i < 32; ++i) { const int kk = 2 * i + (lane >> 5); scr[kk * 33 + (lane & 31)] = (src_c0 >= 0) ? W[(size_t)(k0 + kk) * ldw + src_c0 + (lane & 31)] : 0.f; }
.LBB0_38:
	v_mov_b32_e32 v5, 0
	s_andn2_b64 vcc, exec, s[0:1]
	v_mov_b32_e32 v58, 0
	v_mov_b32_e32 v59, 0
	v_mov_b32_e32 v60, 0
	s_cbranch_vccnz .LBB0_40
	v_or_b32_e32 v58, s13, v21
	v_ashrrev_i32_e32 v59, 31, v58
	v_lshlrev_b64 v[58:59], 13, v[58:59]
	v_lshl_add_u64 v[62:63], v[10:11], 0, v[58:59]
	v_or_b32_e32 v58, s13, v22
	v_ashrrev_i32_e32 v59, 31, v58
	v_lshlrev_b64 v[58:59], 13, v[58:59]
	v_lshl_add_u64 v[64:65], v[10:11], 0, v[58:59]
	v_or_b32_e32 v58, s13, v23
	v_ashrrev_i32_e32 v59, 31, v58
	v_lshlrev_b64 v[58:59], 13, v[58:59]
	v_lshl_add_u64 v[66:67], v[10:11], 0, v[58:59]
	v_or_b32_e32 v58, s13, v24
	v_ashrrev_i32_e32 v59, 31, v58
	v_lshlrev_b64 v[58:59], 13, v[58:59]
	v_lshl_add_u64 v[68:69], v[10:11], 0, v[58:59]
	v_or_b32_e32 v58, s13, v25
	v_ashrrev_i32_e32 v59, 31, v58
	v_lshlrev_b64 v[58:59], 13, v[58:59]
	v_lshl_add_u64 v[70:71], v[10:11], 0, v[58:59]
	v_or_b32_e32 v58, s13, v26
	v_ashrrev_i32_e32 v59, 31, v58
	v_lshlrev_b64 v[58:59], 13, v[58:59]
	v_lshl_add_u64 v[72:73], v[10:11], 0, v[58:59]
	v_or_b32_e32 v58, s13, v27
	v_ashrrev_i32_e32 v59, 31, v58
	v_lshlrev_b64 v[58:59], 13, v[58:59]
	v_lshl_add_u64 v[74:75], v[10:11], 0, v[58:59]
	v_or_b32_e32 v58, s13, v28
	v_ashrrev_i32_e32 v59, 31, v58
	v_lshlrev_b64 v[58:59], 13, v[58:59]
	v_lshl_add_u64 v[76:77], v[10:11], 0, v[58:59]
	global_load_dword v61, v[62:63], off nt
	global_load_dword v78, v[64:65], off nt
	global_load_dword v79, v[66:67], off nt
	global_load_dword v80, v[68:69], off nt
	global_load_dword v5, v[70:71], off nt
	global_load_dword v58, v[72:73], off nt
	global_load_dword v59, v[74:75], off nt
	global_load_dword v60, v[76:77], off nt
	s_waitcnt vmcnt(6)
	ds_write2_b32 v52, v61, v78 offset1:66
	s_waitcnt vmcnt(4)
	ds_write2_b32 v52, v79, v80 offset0:132 offset1:198

; #define LAS __attribute__((address_space(3)))
; __device__ __forceinline__ void wt_item(const float* __restrict__ W, int ldw, int K, int src_c0, bf16_t* __restrict__ WT, int dst_r0, int k0, LAS float* scr, int lane, int Ndst) {
; #pragma unroll 32
;     for (int i = 0; i < 32; ++i) { const int kk = 2 * i + (lane >> 5); scr[kk * 33 + (lane & 31)] = (src_c0 >= 0) ? W[(size_t)(k0 + kk) * ldw + src_c0 + (lane & 31)] : 0.f; }
.LBB0_42:
	v_mov_b32_e32 v5, 0
	s_andn2_b64 vcc, exec, s[0:1]
	v_mov_b32_e32 v58, 0
	v_mov_b32_e32 v59, 0
	v_mov_b32_e32 v60, 0
	s_cbranch_vccnz .LBB0_44
	v_or_b32_e32 v58, s13, v29
	v_ashrrev_i32_e32 v59, 31, v58
	v_lshlrev_b64 v[58:59], 13, v[58:59]
	v_lshl_add_u64 v[62:63], v[10:11], 0, v[58:59]
	v_or_b32_e32 v58, s13, v30
	v_ashrrev_i32_e32 v59, 31, v58
	v_lshlrev_b64 v[58:59], 13, v[58:59]
	v_lshl_add_u64 v[64:65], v[10:11], 0, v[58:59]
	v_or_b32_e32 v58, s13, v31
	v_ashrrev_i32_e32 v59, 31, v58
	v_lshlrev_b64 v[58:59], 13, v[58:59]
	v_lshl_add_u64 v[66:67], v[10:11], 0, v[58:59]
	v_or_b32_e32 v58, s13, v32
	v_ashrrev_i32_e32 v59, 31, v58
	v_lshlrev_b64 v[58:59], 13, v[58:59]
	v_lshl_add_u64 v[68:69], v[10:11], 0, v[58:59]
	v_or_b32_e32 v58, s13, v33
	v_ashrrev_i32_e32 v59, 31, v58
	v_lshlrev_b64 v[58:59], 13, v[58:59]
	v_lshl_add_u64 v[70:71], v[10:11], 0, v[58:59]
	v_or_b32_e32 v58, s13, v34
	v_ashrrev_i32_e32 v59, 31, v58
	v_lshlrev_b64 v[58:59], 13, v[58:59]
	v_lshl_add_u64 v[72:73], v[10:11], 0, v[58:59]
	v_or_b32_e32 v58, s13, v35
	v_ashrrev_i32_e32 v59, 31, v58
	v_lshlrev_b64 v[58:59], 13, v[58:59]
	v_lshl_add_u64 v[74:75], v[10:11], 0, v[58:59]
	v_or_b32_e32 v58, s13, v36
	v_ashrrev_i32_e32 v59, 31, v58
	v_lshlrev_b64 v[58:59], 13, v[58:59]
	v_lshl_add_u64 v[76:77], v[10:11], 0, v[58:59]
	global_load_dword v61, v[62:63], off nt
	global_load_dword v78, v[64:65], off nt
	global_load_dword v79, v[66:67], off nt
	global_load_dword v80, v[68:69], off nt
	global_load_dword v5, v[70:71], off nt
	global_load_dword v58, v[72:73], off nt
	global_load_dword v59, v[74:75], off nt
	global_load_dword v60, v[76:77], off nt
	s_waitcnt vmcnt(6)
	ds_write2_b32 v54, v61, v78 offset1:66
	s_waitcnt vmcnt(4)
	ds_write2_b32 v54, v79, v80 offset0:132 offset1:198

; #define LAS __attribute__((address_space(3)))
; __device__ __forceinline__ void wt_item(const float* __restrict__ W, int ldw, int K, int src_c0, bf16_t* __restrict__ WT, int dst_r0, int k0, LAS float* scr, int lane, int Ndst) {
; #pragma unroll 32
;     for (int i = 0; i < 32; ++i) { const int kk = 2 * i + (lane >> 5); scr[kk * 33 + (lane & 31)] = (src_c0 >= 0) ? W[(size_t)(k0 + kk) * ldw + src_c0 + (lane & 31)] : 0.f; }
.LBB0_46:
	v_mov_b32_e32 v5, 0
	s_andn2_b64 vcc, exec, s[0:1]
	v_mov_b32_e32 v58, 0
	v_mov_b32_e32 v59, 0
	v_mov_b32_e32 v60, 0
	s_cbranch_vccnz .LBB0_31
	v_or_b32_e32 v58, s13, v37
	v_ashrrev_i32_e32 v59, 31, v58
	v_lshlrev_b64 v[58:59], 13, v[58:59]
	v_lshl_add_u64 v[62:63], v[10:11], 0, v[58:59]
	v_or_b32_e32 v58, s13, v38
	v_ashrrev_i32_e32 v59, 31, v58
	v_lshlrev_b64 v[58:59], 13, v[58:59]
	v_lshl_add_u64 v[64:65], v[10:11], 0, v[58:59]
	v_or_b32_e32 v58, s13, v39
	v_ashrrev_i32_e32 v59, 31, v58
	v_lshlrev_b64 v[58:59], 13, v[58:59]
	v_lshl_add_u64 v[66:67], v[10:11], 0, v[58:59]
	v_or_b32_e32 v58, s13, v40
	v_ashrrev_i32_e32 v59, 31, v58
	v_lshlrev_b64 v[58:59], 13, v[58:59]
	v_lshl_add_u64 v[68:69], v[10:11], 0, v[58:59]
	v_or_b32_e32 v58, s13, v41
	v_ashrrev_i32_e32 v59, 31, v58
	v_lshlrev_b64 v[58:59], 13, v[58:59]
	v_lshl_add_u64 v[70:71], v[10:11], 0, v[58:59]
	v_or_b32_e32 v58, s13, v42
	v_ashrrev_i32_e32 v59, 31, v58
	v_lshlrev_b64 v[58:59], 13, v[58:59]
	v_lshl_add_u64 v[72:73], v[10:11], 0, v[58:59]
	v_or_b32_e32 v58, s13, v43
	v_ashrrev_i32_e32 v59, 31, v58
	v_lshlrev_b64 v[58:59], 13, v[58:59]
	v_lshl_add_u64 v[74:75], v[10:11], 0, v[58:59]
	v_or_b32_e32 v58, s13, v44
	v_ashrrev_i32_e32 v59, 31, v58
	v_lshlrev_b64 v[58:59], 13, v[58:59]
	v_lshl_add_u64 v[10:11], v[10:11], 0, v[58:59]
	global_load_dword v61, v[62:63], off nt
	global_load_dword v76, v[64:65], off nt
	global_load_dword v77, v[66:67], off nt
	global_load_dword v78, v[68:69], off nt
	global_load_dword v5, v[70:71], off nt
	global_load_dword v58, v[72:73], off nt
	global_load_dword v59, v[74:75], off nt
	global_load_dword v60, v[10:11], off nt
	v_add_u32_e32 v10, v56, v57
	s_waitcnt vmcnt(6)
	ds_write2_b32 v10, v61, v76 offset1:66
	s_waitcnt vmcnt(4)
	ds_write2_b32 v10, v77, v78 offset0:132 offset1:198
	s_branch .LBB0_31

; #define LAS __attribute__((address_space(3)))
; __device__ __forceinline__ void wt_item(const float* __restrict__ W, int ldw, int K, int src_c0, bf16_t* __restrict__ WT, int dst_r0, int k0, LAS float* scr, int lane, int Ndst) {
; #pragma unroll 32
;     for (int i = 0; i < 32; ++i) { const int kk = 2 * i + (lane >> 5); scr[kk * 33 + (lane & 31)] = (src_c0 >= 0) ? W[(size_t)(k0 + kk) * ldw + src_c0 + (lane & 31)] : 0.f; }
; __device__ __forceinline__ void conv_mla_win(const float* W, bf16_t* WT, LAS float* scr, int gw, int NGW, int lane) {
;     constexpr int nblk = MLA_NP / 32, items = (DM / 64) * nblk;
;     for (int it = gw; it < items; it += NGW) { const int kb = it / nblk, nb = it % nblk;
;         const int src = nb < 32 ? nb * 32 : nb < 96 ? 1088 + (nb - 32) * 32 : nb < 98 ? 1024 + (nb - 96) * 32 : -1;
;         wt_item(W, 3136, DM, src, WT, nb * 32, kb * 64, scr, lane, MLA_NP); }
.LBB0_61:
	s_lshl_b32 s20, s18, 6
	v_lshl_add_u64 v[10:11], s[4:5], 2, v[6:7]
	v_mov_b32_e32 v57, 0
	s_andn2_b64 vcc, exec, s[0:1]
	v_mov_b32_e32 v58, 0
	v_mov_b32_e32 v59, 0
	v_mov_b32_e32 v60, 0
	s_cbranch_vccnz .LBB0_63
	v_or_b32_e32 v57, s20, v13
	v_mad_i64_i32 v[62:63], s[0:1], v57, s14, v[10:11]
	v_or_b32_e32 v57, s20, v14
	v_mad_i64_i32 v[64:65], s[0:1], v57, s14, v[10:11]
	v_or_b32_e32 v57, s20, v15
	v_mad_i64_i32 v[66:67], s[0:1], v57, s14, v[10:11]
	v_or_b32_e32 v57, s20, v16
	v_mad_i64_i32 v[68:69], s[0:1], v57, s14, v[10:11]
	v_or_b32_e32 v57, s20, v17
	v_mad_i64_i32 v[70:71], s[0:1], v57, s14, v[10:11]
	v_or_b32_e32 v57, s20, v18
	v_mad_i64_i32 v[72:73], s[0:1], v57, s14, v[10:11]
	v_or_b32_e32 v57, s20, v19
	v_mad_i64_i32 v[74:75], s[0:1], v57, s14, v[10:11]
	v_or_b32_e32 v57, s20, v20
	v_mad_i64_i32 v[76:77], s[0:1], v57, s14, v[10:11]
	global_load_dword v61, v[62:63], off nt
	global_load_dword v78, v[64:65], off nt
	global_load_dword v79, v[66:67], off nt
	global_load_dword v80, v[68:69], off nt
	global_load_dword v57, v[70:71], off nt
	global_load_dword v58, v[72:73], off nt
	global_load_dword v59, v[74:75], off nt
	global_load_dword v60, v[76:77], off nt
	s_waitcnt vmcnt(6)
	ds_write2_b32 v50, v61, v78 offset1:66
	s_waitcnt vmcnt(4)
	ds_write2_b32 v50, v79, v80 offset0:132 offset1:198

; #define LAS __attribute__((address_space(3)))
; __device__ __forceinline__ void wt_item(const float* __restrict__ W, int ldw, int K, int src_c0, bf16_t* __restrict__ WT, int dst_r0, int k0, LAS float* scr, int lane, int Ndst) {
; #pragma unroll 32
;     for (int i = 0; i < 32; ++i) { const int kk = 2 * i + (lane >> 5); scr[kk * 33 + (lane & 31)] = (src_c0 >= 0) ? W[(size_t)(k0 + kk) * ldw + src_c0 + (lane & 31)] : 0.f; }
.LBB0_65:
	v_mov_b32_e32 v57, 0
	s_andn2_b64 vcc, exec, s[0:1]
	v_mov_b32_e32 v58, 0
	v_mov_b32_e32 v59, 0
	v_mov_b32_e32 v60, 0
	s_cbranch_vccnz .LBB0_67
	v_or_b32_e32 v57, s20, v21
	v_mad_i64_i32 v[62:63], s[0:1], v57, s14, v[10:11]
	v_or_b32_e32 v57, s20, v22
	v_mad_i64_i32 v[64:65], s[0:1], v57, s14, v[10:11]
	v_or_b32_e32 v57, s20, v23
	v_mad_i64_i32 v[66:67], s[0:1], v57, s14, v[10:11]
	v_or_b32_e32 v57, s20, v24
	v_mad_i64_i32 v[68:69], s[0:1], v57, s14, v[10:11]
	v_or_b32_e32 v57, s20, v25
	v_mad_i64_i32 v[70:71], s[0:1], v57, s14, v[10:11]
	v_or_b32_e32 v57, s20, v26
	v_mad_i64_i32 v[72:73], s[0:1], v57, s14, v[10:11]
	v_or_b32_e32 v57, s20, v27
	v_mad_i64_i32 v[74:75], s[0:1], v57, s14, v[10:11]
	v_or_b32_e32 v57, s20, v28
	v_mad_i64_i32 v[76:77], s[0:1], v57, s14, v[10:11]
	global_load_dword v61, v[62:63], off nt
	global_load_dword v78, v[64:65], off nt
	global_load_dword v79, v[66:67], off nt
	global_load_dword v80, v[68:69], off nt
	global_load_dword v57, v[70:71], off nt
	global_load_dword v58, v[72:73], off nt
	global_load_dword v59, v[74:75], off nt
	global_load_dword v60, v[76:77], off nt
	s_waitcnt vmcnt(6)
	ds_write2_b32 v52, v61, v78 offset1:66
	s_waitcnt vmcnt(4)
	ds_write2_b32 v52, v79, v80 offset0:132 offset1:198

; #define LAS __attribute__((address_space(3)))
; __device__ __forceinline__ void wt_item(const float* __restrict__ W, int ldw, int K, int src_c0, bf16_t* __restrict__ WT, int dst_r0, int k0, LAS float* scr, int lane, int Ndst) {
; #pragma unroll 32
;     for (int i = 0; i < 32; ++i) { const int kk = 2 * i + (lane >> 5); scr[kk * 33 + (lane & 31)] = (src_c0 >= 0) ? W[(size_t)(k0 + kk) * ldw + src_c0 + (lane & 31)] : 0.f; }
.LBB0_69:
	v_mov_b32_e32 v57, 0
	s_andn2_b64 vcc, exec, s[0:1]
	v_mov_b32_e32 v58, 0
	v_mov_b32_e32 v59, 0
	v_mov_b32_e32 v60, 0
	s_cbranch_vccnz .LBB0_71
	v_or_b32_e32 v57, s20, v29
	v_mad_i64_i32 v[62:63], s[0:1], v57, s14, v[10:11]
	v_or_b32_e32 v57, s20, v30
	v_mad_i64_i32 v[64:65], s[0:1], v57, s14, v[10:11]
	v_or_b32_e32 v57, s20, v31
	v_mad_i64_i32 v[66:67], s[0:1], v57, s14, v[10:11]
	v_or_b32_e32 v57, s20, v32
	v_mad_i64_i32 v[68:69], s[0:1], v57, s14, v[10:11]
	v_or_b32_e32 v57, s20, v33
	v_mad_i64_i32 v[70:71], s[0:1], v57, s14, v[10:11]
	v_or_b32_e32 v57, s20, v34
	v_mad_i64_i32 v[72:73], s[0:1], v57, s14, v[10:11]
	v_or_b32_e32 v57, s20, v35
	v_mad_i64_i32 v[74:75], s[0:1], v57, s14, v[10:11]
	v_or_b32_e32 v57, s20, v36
	v_mad_i64_i32 v[76:77], s[0:1], v57, s14, v[10:11]
	global_load_dword v61, v[62:63], off nt
	global_load_dword v78, v[64:65], off nt
	global_load_dword v79, v[66:67], off nt
	global_load_dword v80, v[68:69], off nt
	global_load_dword v57, v[70:71], off nt
	global_load_dword v58, v[72:73], off nt
	global_load_dword v59, v[74:75], off nt
	global_load_dword v60, v[76:77], off nt
	s_waitcnt vmcnt(6)
	ds_write2_b32 v54, v61, v78 offset1:66
	s_waitcnt vmcnt(4)
	ds_write2_b32 v54, v79, v80 offset0:132 offset1:198

; #define LAS __attribute__((address_space(3)))
; __device__ __forceinline__ void wt_item(const float* __restrict__ W, int ldw, int K, int src_c0, bf16_t* __restrict__ WT, int dst_r0, int k0, LAS float* scr, int lane, int Ndst) {
; #pragma unroll 32
;     for (int i = 0; i < 32; ++i) { const int kk = 2 * i + (lane >> 5); scr[kk * 33 + (lane & 31)] = (src_c0 >= 0) ? W[(size_t)(k0 + kk) * ldw + src_c0 + (lane & 31)] : 0.f; }
.LBB0_73:
	v_mov_b32_e32 v57, 0
	s_andn2_b64 vcc, exec, s[0:1]
	v_mov_b32_e32 v58, 0
	v_mov_b32_e32 v59, 0
	v_mov_b32_e32 v60, 0
	s_cbranch_vccnz .LBB0_50
	v_or_b32_e32 v57, s20, v37
	v_mad_i64_i32 v[62:63], s[0:1], v57, s14, v[10:11]
	v_or_b32_e32 v57, s20, v38
	v_mad_i64_i32 v[64:65], s[0:1], v57, s14, v[10:11]
	v_or_b32_e32 v57, s20, v39
	v_mad_i64_i32 v[66:67], s[0:1], v57, s14, v[10:11]
	v_or_b32_e32 v57, s20, v40
	v_mad_i64_i32 v[68:69], s[0:1], v57, s14, v[10:11]
	v_or_b32_e32 v57, s20, v41
	v_mad_i64_i32 v[70:71], s[0:1], v57, s14, v[10:11]
	v_or_b32_e32 v57, s20, v42
	v_mad_i64_i32 v[72:73], s[0:1], v57, s14, v[10:11]
	v_or_b32_e32 v57, s20, v43
	v_mad_i64_i32 v[74:75], s[0:1], v57, s14, v[10:11]
	v_or_b32_e32 v57, s20, v44
	v_mad_i64_i32 v[10:11], s[0:1], v57, s14, v[10:11]
	global_load_dword v61, v[62:63], off nt
	global_load_dword v76, v[64:65], off nt
	global_load_dword v77, v[66:67], off nt
	global_load_dword v78, v[68:69], off nt
	global_load_dword v57, v[70:71], off nt
	global_load_dword v58, v[72:73], off nt
	global_load_dword v59, v[74:75], off nt
	global_load_dword v60, v[10:11], off nt
	s_waitcnt vmcnt(6)
	ds_write2_b32 v56, v61, v76 offset1:66
	s_waitcnt vmcnt(4)
	ds_write2_b32 v56, v77, v78 offset0:132 offset1:198
	s_branch .LBB0_50

; #define LAS __attribute__((address_space(3)))
; __device__ __forceinline__ void wt_item(const float* __restrict__ W, int ldw, int K, int src_c0, bf16_t* __restrict__ WT, int dst_r0, int k0, LAS float* scr, int lane, int Ndst) {
; #pragma unroll 32
;     for (int i = 0; i < 32; ++i) { const int kk = 2 * i + (lane >> 5); scr[kk * 33 + (lane & 31)] = (src_c0 >= 0) ? W[(size_t)(k0 + kk) * ldw + src_c0 + (lane & 31)] : 0.f; }
; __device__ __forceinline__ void conv_plain(const float* W, int K, int N, bf16_t* WT, LAS float* scr, int gw, int NGW, int lane) {
;     const int nblk = N / 32, items = (K / 64) * nblk;
;     for (int it = gw; it < items; it += NGW) { const int kb = it / nblk, nb = it % nblk; wt_item(W, N, K, nb * 32, WT, nb * 32, kb * 64, scr, lane, N); }
.LBB0_80:
	s_mul_i32 s4, s18, 0xfffff400
	s_add_i32 s4, s12, s4
	s_lshl_b32 s19, s18, 6
	v_lshl_add_u64 v[10:11], s[4:5], 2, v[6:7]
	v_mov_b32_e32 v57, 0
	s_andn2_b64 vcc, exec, s[0:1]
	v_mov_b32_e32 v58, 0
	v_mov_b32_e32 v59, 0
	v_mov_b32_e32 v60, 0
	s_cbranch_vccnz .LBB0_82
	v_or_b32_e32 v57, s19, v13
	v_mad_i64_i32 v[62:63], s[0:1], v57, s14, v[10:11]
	v_or_b32_e32 v57, s19, v14
	v_mad_i64_i32 v[64:65], s[0:1], v57, s14, v[10:11]
	v_or_b32_e32 v57, s19, v15
	v_mad_i64_i32 v[66:67], s[0:1], v57, s14, v[10:11]
	v_or_b32_e32 v57, s19, v16
	v_mad_i64_i32 v[68:69], s[0:1], v57, s14, v[10:11]
	v_or_b32_e32 v57, s19, v17
	v_mad_i64_i32 v[70:71], s[0:1], v57, s14, v[10:11]
	v_or_b32_e32 v57, s19, v18
	v_mad_i64_i32 v[72:73], s[0:1], v57, s14, v[10:11]
	v_or_b32_e32 v57, s19, v19
	v_mad_i64_i32 v[74:75], s[0:1], v57, s14, v[10:11]
	v_or_b32_e32 v57, s19, v20
	v_mad_i64_i32 v[76:77], s[0:1], v57, s14, v[10:11]
	global_load_dword v61, v[62:63], off nt
	global_load_dword v78, v[64:65], off nt
	global_load_dword v79, v[66:67], off nt
	global_load_dword v80, v[68:69], off nt
	global_load_dword v57, v[70:71], off nt
	global_load_dword v58, v[72:73], off nt
	global_load_dword v59, v[74:75], off nt
	global_load_dword v60, v[76:77], off nt
	s_waitcnt vmcnt(6)
	ds_write2_b32 v50, v61, v78 offset1:66
	s_waitcnt vmcnt(4)
	ds_write2_b32 v50, v79, v80 offset0:132 offset1:198

; #define LAS __attribute__((address_space(3)))
; __device__ __forceinline__ void wt_item(const float* __restrict__ W, int ldw, int K, int src_c0, bf16_t* __restrict__ WT, int dst_r0, int k0, LAS float* scr, int lane, int Ndst) {
; #pragma unroll 32
;     for (int i = 0; i < 32; ++i) { const int kk = 2 * i + (lane >> 5); scr[kk * 33 + (lane & 31)] = (src_c0 >= 0) ? W[(size_t)(k0 + kk) * ldw + src_c0 + (lane & 31)] : 0.f; }
.LBB0_84:
	v_mov_b32_e32 v57, 0
	s_andn2_b64 vcc, exec, s[0:1]
	v_mov_b32_e32 v58, 0
	v_mov_b32_e32 v59, 0
	v_mov_b32_e32 v60, 0
	s_cbranch_vccnz .LBB0_86
	v_or_b32_e32 v57, s19, v21
	v_mad_i64_i32 v[62:63], s[0:1], v57, s14, v[10:11]
	v_or_b32_e32 v57, s19, v22
	v_mad_i64_i32 v[64:65], s[0:1], v57, s14, v[10:11]
	v_or_b32_e32 v57, s19, v23
	v_mad_i64_i32 v[66:67], s[0:1], v57, s14, v[10:11]
	v_or_b32_e32 v57, s19, v24
	v_mad_i64_i32 v[68:69], s[0:1], v57, s14, v[10:11]
	v_or_b32_e32 v57, s19, v25
	v_mad_i64_i32 v[70:71], s[0:1], v57, s14, v[10:11]
	v_or_b32_e32 v57, s19, v26
	v_mad_i64_i32 v[72:73], s[0:1], v57, s14, v[10:11]
	v_or_b32_e32 v57, s19, v27
	v_mad_i64_i32 v[74:75], s[0:1], v57, s14, v[10:11]
	v_or_b32_e32 v57, s19, v28
	v_mad_i64_i32 v[76:77], s[0:1], v57, s14, v[10:11]
	global_load_dword v61, v[62:63], off nt
	global_load_dword v78, v[64:65], off nt
	global_load_dword v79, v[66:67], off nt
	global_load_dword v80, v[68:69], off nt
	global_load_dword v57, v[70:71], off nt
	global_load_dword v58, v[72:73], off nt
	global_load_dword v59, v[74:75], off nt
	global_load_dword v60, v[76:77], off nt
	s_waitcnt vmcnt(6)
	ds_write2_b32 v52, v61, v78 offset1:66
	s_waitcnt vmcnt(4)
	ds_write2_b32 v52, v79, v80 offset0:132 offset1:198

; #define LAS __attribute__((address_space(3)))
; __device__ __forceinline__ void wt_item(const float* __restrict__ W, int ldw, int K, int src_c0, bf16_t* __restrict__ WT, int dst_r0, int k0, LAS float* scr, int lane, int Ndst) {
; #pragma unroll 32
;     for (int i = 0; i < 32; ++i) { const int kk = 2 * i + (lane >> 5); scr[kk * 33 + (lane & 31)] = (src_c0 >= 0) ? W[(size_t)(k0 + kk) * ldw + src_c0 + (lane & 31)] : 0.f; }
.LBB0_88:
	v_mov_b32_e32 v57, 0
	s_andn2_b64 vcc, exec, s[0:1]
	v_mov_b32_e32 v58, 0
	v_mov_b32_e32 v59, 0
	v_mov_b32_e32 v60, 0
	s_cbranch_vccnz .LBB0_90
	v_or_b32_e32 v57, s19, v29
	v_mad_i64_i32 v[62:63], s[0:1], v57, s14, v[10:11]
	v_or_b32_e32 v57, s19, v30
	v_mad_i64_i32 v[64:65], s[0:1], v57, s14, v[10:11]
	v_or_b32_e32 v57, s19, v31
	v_mad_i64_i32 v[66:67], s[0:1], v57, s14, v[10:11]
	v_or_b32_e32 v57, s19, v32
	v_mad_i64_i32 v[68:69], s[0:1], v57, s14, v[10:11]
	v_or_b32_e32 v57, s19, v33
	v_mad_i64_i32 v[70:71], s[0:1], v57, s14, v[10:11]
	v_or_b32_e32 v57, s19, v34
	v_mad_i64_i32 v[72:73], s[0:1], v57, s14, v[10:11]
	v_or_b32_e32 v57, s19, v35
	v_mad_i64_i32 v[74:75], s[0:1], v57, s14, v[10:11]
	v_or_b32_e32 v57, s19, v36
	v_mad_i64_i32 v[76:77], s[0:1], v57, s14, v[10:11]
	global_load_dword v61, v[62:63], off nt
	global_load_dword v78, v[64:65], off nt
	global_load_dword v79, v[66:67], off nt
	global_load_dword v80, v[68:69], off nt
	global_load_dword v57, v[70:71], off nt
	global_load_dword v58, v[72:73], off nt
	global_load_dword v59, v[74:75], off nt
	global_load_dword v60, v[76:77], off nt
	s_waitcnt vmcnt(6)
	ds_write2_b32 v54, v61, v78 offset1:66
	s_waitcnt vmcnt(4)
	ds_write2_b32 v54, v79, v80 offset0:132 offset1:198

; #define LAS __attribute__((address_space(3)))
; __device__ __forceinline__ void wt_item(const float* __restrict__ W, int ldw, int K, int src_c0, bf16_t* __restrict__ WT, int dst_r0, int k0, LAS float* scr, int lane, int Ndst) {
; #pragma unroll 32
;     for (int i = 0; i < 32; ++i) { const int kk = 2 * i + (lane >> 5); scr[kk * 33 + (lane & 31)] = (src_c0 >= 0) ? W[(size_t)(k0 + kk) * ldw + src_c0 + (lane & 31)] : 0.f; }
.LBB0_92:
	v_mov_b32_e32 v57, 0
	s_andn2_b64 vcc, exec, s[0:1]
	v_mov_b32_e32 v58, 0
	v_mov_b32_e32 v59, 0
	v_mov_b32_e32 v60, 0
	s_cbranch_vccnz .LBB0_77
	v_or_b32_e32 v57, s19, v37
	v_mad_i64_i32 v[62:63], s[0:1], v57, s14, v[10:11]
	v_or_b32_e32 v57, s19, v38
	v_mad_i64_i32 v[64:65], s[0:1], v57, s14, v[10:11]
	v_or_b32_e32 v57, s19, v39
	v_mad_i64_i32 v[66:67], s[0:1], v57, s14, v[10:11]
	v_or_b32_e32 v57, s19, v40
	v_mad_i64_i32 v[68:69], s[0:1], v57, s14, v[10:11]
	v_or_b32_e32 v57, s19, v41
	v_mad_i64_i32 v[70:71], s[0:1], v57, s14, v[10:11]
	v_or_b32_e32 v57, s19, v42
	v_mad_i64_i32 v[72:73], s[0:1], v57, s14, v[10:11]
	v_or_b32_e32 v57, s19, v43
	v_mad_i64_i32 v[74:75], s[0:1], v57, s14, v[10:11]
	v_or_b32_e32 v57, s19, v44
	v_mad_i64_i32 v[10:11], s[0:1], v57, s14, v[10:11]
	global_load_dword v61, v[62:63], off nt
	global_load_dword v76, v[64:65], off nt
	global_load_dword v77, v[66:67], off nt
	global_load_dword v78, v[68:69], off nt
	global_load_dword v57, v[70:71], off nt
	global_load_dword v58, v[72:73], off nt
	global_load_dword v59, v[74:75], off nt
	global_load_dword v60, v[10:11], off nt
	s_waitcnt vmcnt(6)
	ds_write2_b32 v56, v61, v76 offset1:66
	s_waitcnt vmcnt(4)
	ds_write2_b32 v56, v77, v78 offset0:132 offset1:198
	s_branch .LBB0_77

; #define LAS __attribute__((address_space(3)))
; __device__ __forceinline__ void wt_item(const float* __restrict__ W, int ldw, int K, int src_c0, bf16_t* __restrict__ WT, int dst_r0, int k0, LAS float* scr, int lane, int Ndst) {
; #pragma unroll 32
;     for (int i = 0; i < 32; ++i) { const int kk = 2 * i + (lane >> 5); scr[kk * 33 + (lane & 31)] = (src_c0 >= 0) ? W[(size_t)(k0 + kk) * ldw + src_c0 + (lane & 31)] : 0.f; }
; __device__ __forceinline__ void conv_plain(const float* W, int K, int N, bf16_t* WT, LAS float* scr, int gw, int NGW, int lane) {
;     const int nblk = N / 32, items = (K / 64) * nblk;
;     for (int it = gw; it < items; it += NGW) { const int kb = it / nblk, nb = it % nblk; wt_item(W, N, K, nb * 32, WT, nb * 32, kb * 64, scr, lane, N); }
.LBB0_99:
	s_ashr_i32 s12, s4, 7
	s_lshl_b32 s4, s12, 12
	s_sub_i32 s4, s16, s4
	s_lshl_b32 s13, s12, 6
	v_lshl_add_u64 v[10:11], s[4:5], 2, v[6:7]
	v_mov_b32_e32 v5, 0
	s_andn2_b64 vcc, exec, s[0:1]
	v_mov_b32_e32 v57, 0
	v_mov_b32_e32 v58, 0
	v_mov_b32_e32 v59, 0
	s_cbranch_vccnz .LBB0_101
	v_or_b32_e32 v58, s13, v13
	v_ashrrev_i32_e32 v59, 31, v58
	v_lshlrev_b64 v[58:59], 14, v[58:59]
	v_lshl_add_u64 v[60:61], v[10:11], 0, v[58:59]
	v_or_b32_e32 v58, s13, v14
	v_ashrrev_i32_e32 v59, 31, v58
	v_lshlrev_b64 v[58:59], 14, v[58:59]
	v_lshl_add_u64 v[62:63], v[10:11], 0, v[58:59]
	v_or_b32_e32 v58, s13, v15
	v_ashrrev_i32_e32 v59, 31, v58
	v_lshlrev_b64 v[58:59], 14, v[58:59]
	v_lshl_add_u64 v[64:65], v[10:11], 0, v[58:59]
	v_or_b32_e32 v58, s13, v16
	v_ashrrev_i32_e32 v59, 31, v58
	v_lshlrev_b64 v[58:59], 14, v[58:59]
	v_lshl_add_u64 v[66:67], v[10:11], 0, v[58:59]
	v_or_b32_e32 v58, s13, v17
	v_ashrrev_i32_e32 v59, 31, v58
	v_lshlrev_b64 v[58:59], 14, v[58:59]
	v_lshl_add_u64 v[68:69], v[10:11], 0, v[58:59]
	v_or_b32_e32 v58, s13, v18
	v_ashrrev_i32_e32 v59, 31, v58
	v_lshlrev_b64 v[58:59], 14, v[58:59]
	v_lshl_add_u64 v[70:71], v[10:11], 0, v[58:59]
	v_or_b32_e32 v58, s13, v19
	v_ashrrev_i32_e32 v59, 31, v58
	v_lshlrev_b64 v[58:59], 14, v[58:59]
	v_lshl_add_u64 v[72:73], v[10:11], 0, v[58:59]
	v_or_b32_e32 v58, s13, v20
	v_ashrrev_i32_e32 v59, 31, v58
	v_lshlrev_b64 v[58:59], 14, v[58:59]
	v_lshl_add_u64 v[74:75], v[10:11], 0, v[58:59]
	global_load_dword v76, v[60:61], off nt
	global_load_dword v77, v[62:63], off nt
	global_load_dword v78, v[64:65], off nt
	global_load_dword v79, v[66:67], off nt
	global_load_dword v5, v[68:69], off nt
	global_load_dword v57, v[70:71], off nt
	global_load_dword v58, v[72:73], off nt
	global_load_dword v59, v[74:75], off nt
	s_waitcnt vmcnt(6)
	ds_write2_b32 v50, v76, v77 offset1:66
	s_waitcnt vmcnt(4)
	ds_write2_b32 v50, v78, v79 offset0:132 offset1:198

; #define LAS __attribute__((address_space(3)))
; __device__ __forceinline__ void wt_item(const float* __restrict__ W, int ldw, int K, int src_c0, bf16_t* __restrict__ WT, int dst_r0, int k0, LAS float* scr, int lane, int Ndst) {
; #pragma unroll 32
;     for (int i = 0; i < 32; ++i) { const int kk = 2 * i + (lane >> 5); scr[kk * 33 + (lane & 31)] = (src_c0 >= 0) ? W[(size_t)(k0 + kk) * ldw + src_c0 + (lane & 31)] : 0.f; }
.LBB0_103:
	v_mov_b32_e32 v5, 0
	s_andn2_b64 vcc, exec, s[0:1]
	v_mov_b32_e32 v57, 0
	v_mov_b32_e32 v58, 0
	v_mov_b32_e32 v59, 0
	s_cbranch_vccnz .LBB0_105
	v_or_b32_e32 v58, s13, v21
	v_ashrrev_i32_e32 v59, 31, v58
	v_lshlrev_b64 v[58:59], 14, v[58:59]
	v_lshl_add_u64 v[60:61], v[10:11], 0, v[58:59]
	v_or_b32_e32 v58, s13, v22
	v_ashrrev_i32_e32 v59, 31, v58
	v_lshlrev_b64 v[58:59], 14, v[58:59]
	v_lshl_add_u64 v[62:63], v[10:11], 0, v[58:59]
	v_or_b32_e32 v58, s13, v23
	v_ashrrev_i32_e32 v59, 31, v58
	v_lshlrev_b64 v[58:59], 14, v[58:59]
	v_lshl_add_u64 v[64:65], v[10:11], 0, v[58:59]
	v_or_b32_e32 v58, s13, v24
	v_ashrrev_i32_e32 v59, 31, v58
	v_lshlrev_b64 v[58:59], 14, v[58:59]
	v_lshl_add_u64 v[66:67], v[10:11], 0, v[58:59]
	v_or_b32_e32 v58, s13, v25
	v_ashrrev_i32_e32 v59, 31, v58
	v_lshlrev_b64 v[58:59], 14, v[58:59]
	v_lshl_add_u64 v[68:69], v[10:11], 0, v[58:59]
	v_or_b32_e32 v58, s13, v26
	v_ashrrev_i32_e32 v59, 31, v58
	v_lshlrev_b64 v[58:59], 14, v[58:59]
	v_lshl_add_u64 v[70:71], v[10:11], 0, v[58:59]
	v_or_b32_e32 v58, s13, v27
	v_ashrrev_i32_e32 v59, 31, v58
	v_lshlrev_b64 v[58:59], 14, v[58:59]
	v_lshl_add_u64 v[72:73], v[10:11], 0, v[58:59]
	v_or_b32_e32 v58, s13, v28
	v_ashrrev_i32_e32 v59, 31, v58
	v_lshlrev_b64 v[58:59], 14, v[58:59]
	v_lshl_add_u64 v[74:75], v[10:11], 0, v[58:59]
	global_load_dword v76, v[60:61], off nt
	global_load_dword v77, v[62:63], off nt
	global_load_dword v78, v[64:65], off nt
	global_load_dword v79, v[66:67], off nt
	global_load_dword v5, v[68:69], off nt
	global_load_dword v57, v[70:71], off nt
	global_load_dword v58, v[72:73], off nt
	global_load_dword v59, v[74:75], off nt
	s_waitcnt vmcnt(6)
	ds_write2_b32 v52, v76, v77 offset1:66
	s_waitcnt vmcnt(4)
	ds_write2_b32 v52, v78, v79 offset0:132 offset1:198

; #define LAS __attribute__((address_space(3)))
; __device__ __forceinline__ void wt_item(const float* __restrict__ W, int ldw, int K, int src_c0, bf16_t* __restrict__ WT, int dst_r0, int k0, LAS float* scr, int lane, int Ndst) {
; #pragma unroll 32
;     for (int i = 0; i < 32; ++i) { const int kk = 2 * i + (lane >> 5); scr[kk * 33 + (lane & 31)] = (src_c0 >= 0) ? W[(size_t)(k0 + kk) * ldw + src_c0 + (lane & 31)] : 0.f; }
.LBB0_107:
	v_mov_b32_e32 v5, 0
	s_andn2_b64 vcc, exec, s[0:1]
	v_mov_b32_e32 v57, 0
	v_mov_b32_e32 v58, 0
	v_mov_b32_e32 v59, 0
	s_cbranch_vccnz .LBB0_109
	v_or_b32_e32 v58, s13, v29
	v_ashrrev_i32_e32 v59, 31, v58
	v_lshlrev_b64 v[58:59], 14, v[58:59]
	v_lshl_add_u64 v[60:61], v[10:11], 0, v[58:59]
	v_or_b32_e32 v58, s13, v30
	v_ashrrev_i32_e32 v59, 31, v58
	v_lshlrev_b64 v[58:59], 14, v[58:59]
	v_lshl_add_u64 v[62:63], v[10:11], 0, v[58:59]
	v_or_b32_e32 v58, s13, v31
	v_ashrrev_i32_e32 v59, 31, v58
	v_lshlrev_b64 v[58:59], 14, v[58:59]
	v_lshl_add_u64 v[64:65], v[10:11], 0, v[58:59]
	v_or_b32_e32 v58, s13, v32
	v_ashrrev_i32_e32 v59, 31, v58
	v_lshlrev_b64 v[58:59], 14, v[58:59]
	v_lshl_add_u64 v[66:67], v[10:11], 0, v[58:59]
	v_or_b32_e32 v58, s13, v33
	v_ashrrev_i32_e32 v59, 31, v58
	v_lshlrev_b64 v[58:59], 14, v[58:59]
	v_lshl_add_u64 v[68:69], v[10:11], 0, v[58:59]
	v_or_b32_e32 v58, s13, v34
	v_ashrrev_i32_e32 v59, 31, v58
	v_lshlrev_b64 v[58:59], 14, v[58:59]
	v_lshl_add_u64 v[70:71], v[10:11], 0, v[58:59]
	v_or_b32_e32 v58, s13, v35
	v_ashrrev_i32_e32 v59, 31, v58
	v_lshlrev_b64 v[58:59], 14, v[58:59]
	v_lshl_add_u64 v[72:73], v[10:11], 0, v[58:59]
	v_or_b32_e32 v58, s13, v36
	v_ashrrev_i32_e32 v59, 31, v58
	v_lshlrev_b64 v[58:59], 14, v[58:59]
	v_lshl_add_u64 v[74:75], v[10:11], 0, v[58:59]
	global_load_dword v76, v[60:61], off nt
	global_load_dword v77, v[62:63], off nt
	global_load_dword v78, v[64:65], off nt
	global_load_dword v79, v[66:67], off nt
	global_load_dword v5, v[68:69], off nt
	global_load_dword v57, v[70:71], off nt
	global_load_dword v58, v[72:73], off nt
	global_load_dword v59, v[74:75], off nt
	s_waitcnt vmcnt(6)
	ds_write2_b32 v54, v76, v77 offset1:66
	s_waitcnt vmcnt(4)
	ds_write2_b32 v54, v78, v79 offset0:132 offset1:198

; #define LAS __attribute__((address_space(3)))
; __device__ __forceinline__ void wt_item(const float* __restrict__ W, int ldw, int K, int src_c0, bf16_t* __restrict__ WT, int dst_r0, int k0, LAS float* scr, int lane, int Ndst) {
; #pragma unroll 32
;     for (int i = 0; i < 32; ++i) { const int kk = 2 * i + (lane >> 5); scr[kk * 33 + (lane & 31)] = (src_c0 >= 0) ? W[(size_t)(k0 + kk) * ldw + src_c0 + (lane & 31)] : 0.f; }
.LBB0_111:
	v_mov_b32_e32 v5, 0
	s_andn2_b64 vcc, exec, s[0:1]
	v_mov_b32_e32 v57, 0
	v_mov_b32_e32 v58, 0
	v_mov_b32_e32 v59, 0
	s_cbranch_vccnz .LBB0_96
	v_or_b32_e32 v58, s13, v37
	v_ashrrev_i32_e32 v59, 31, v58
	v_lshlrev_b64 v[58:59], 14, v[58:59]
	v_lshl_add_u64 v[60:61], v[10:11], 0, v[58:59]
	v_or_b32_e32 v58, s13, v38
	v_ashrrev_i32_e32 v59, 31, v58
	v_lshlrev_b64 v[58:59], 14, v[58:59]
	v_lshl_add_u64 v[62:63], v[10:11], 0, v[58:59]
	v_or_b32_e32 v58, s13, v39
	v_ashrrev_i32_e32 v59, 31, v58
	v_lshlrev_b64 v[58:59], 14, v[58:59]
	v_lshl_add_u64 v[64:65], v[10:11], 0, v[58:59]
	v_or_b32_e32 v58, s13, v40
	v_ashrrev_i32_e32 v59, 31, v58
	v_lshlrev_b64 v[58:59], 14, v[58:59]
	v_lshl_add_u64 v[66:67], v[10:11], 0, v[58:59]
	v_or_b32_e32 v58, s13, v41
	v_ashrrev_i32_e32 v59, 31, v58
	v_lshlrev_b64 v[58:59], 14, v[58:59]
	v_lshl_add_u64 v[68:69], v[10:11], 0, v[58:59]
	v_or_b32_e32 v58, s13, v42
	v_ashrrev_i32_e32 v59, 31, v58
	v_lshlrev_b64 v[58:59], 14, v[58:59]
	v_lshl_add_u64 v[70:71], v[10:11], 0, v[58:59]
	v_or_b32_e32 v58, s13, v43
	v_ashrrev_i32_e32 v59, 31, v58
	v_lshlrev_b64 v[58:59], 14, v[58:59]
	v_lshl_add_u64 v[72:73], v[10:11], 0, v[58:59]
	v_or_b32_e32 v58, s13, v44
	v_ashrrev_i32_e32 v59, 31, v58
	v_lshlrev_b64 v[58:59], 14, v[58:59]
	v_lshl_add_u64 v[10:11], v[10:11], 0, v[58:59]
	global_load_dword v74, v[60:61], off nt
	global_load_dword v75, v[62:63], off nt
	global_load_dword v76, v[64:65], off nt
	global_load_dword v77, v[66:67], off nt
	global_load_dword v5, v[68:69], off nt
	global_load_dword v57, v[70:71], off nt
	global_load_dword v58, v[72:73], off nt
	global_load_dword v59, v[10:11], off nt
	s_waitcnt vmcnt(6)
	ds_write2_b32 v56, v74, v75 offset1:66
	s_waitcnt vmcnt(4)
	ds_write2_b32 v56, v76, v77 offset0:132 offset1:198
	s_branch .LBB0_96

; #define LAS __attribute__((address_space(3)))
; __device__ __forceinline__ void wt_item(const float* __restrict__ W, int ldw, int K, int src_c0, bf16_t* __restrict__ WT, int dst_r0, int k0, LAS float* scr, int lane, int Ndst) {
; #pragma unroll 32
;     for (int i = 0; i < 32; ++i) { const int kk = 2 * i + (lane >> 5); scr[kk * 33 + (lane & 31)] = (src_c0 >= 0) ? W[(size_t)(k0 + kk) * ldw + src_c0 + (lane & 31)] : 0.f; }
; __device__ __forceinline__ void conv_plain(const float* W, int K, int N, bf16_t* WT, LAS float* scr, int gw, int NGW, int lane) {
;     const int nblk = N / 32, items = (K / 64) * nblk;
;     for (int it = gw; it < items; it += NGW) { const int kb = it / nblk, nb = it % nblk; wt_item(W, N, K, nb * 32, WT, nb * 32, kb * 64, scr, lane, N); }
.LBB0_118:
	s_ashr_i32 s6, s4, 6
	s_lshl_b32 s4, s6, 11
	s_sub_i32 s4, s12, s4
	v_lshl_add_u64 v[8:9], s[4:5], 2, v[6:7]
	v_mov_b32_e32 v2, 0
	s_andn2_b64 vcc, exec, s[0:1]
	v_mov_b32_e32 v10, 0
	v_mov_b32_e32 v11, 0
	v_mov_b32_e32 v58, 0
	s_cbranch_vccnz .LBB0_120
	v_or_b32_e32 v10, s7, v13
	v_ashrrev_i32_e32 v11, 31, v10
	v_lshlrev_b64 v[10:11], 13, v[10:11]
	v_lshl_add_u64 v[60:61], v[8:9], 0, v[10:11]
	v_or_b32_e32 v10, s7, v14
	v_ashrrev_i32_e32 v11, 31, v10
	v_lshlrev_b64 v[10:11], 13, v[10:11]
	v_lshl_add_u64 v[62:63], v[8:9], 0, v[10:11]
	v_or_b32_e32 v10, s7, v15
	v_ashrrev_i32_e32 v11, 31, v10
	v_lshlrev_b64 v[10:11], 13, v[10:11]
	v_lshl_add_u64 v[64:65], v[8:9], 0, v[10:11]
	v_or_b32_e32 v10, s7, v16
	v_ashrrev_i32_e32 v11, 31, v10
	v_lshlrev_b64 v[10:11], 13, v[10:11]
	v_lshl_add_u64 v[66:67], v[8:9], 0, v[10:11]
	v_or_b32_e32 v10, s7, v17
	v_ashrrev_i32_e32 v11, 31, v10
	v_lshlrev_b64 v[10:11], 13, v[10:11]
	v_lshl_add_u64 v[68:69], v[8:9], 0, v[10:11]
	v_or_b32_e32 v10, s7, v18
	v_ashrrev_i32_e32 v11, 31, v10
	v_lshlrev_b64 v[10:11], 13, v[10:11]
	v_lshl_add_u64 v[70:71], v[8:9], 0, v[10:11]
	v_or_b32_e32 v10, s7, v19
	v_ashrrev_i32_e32 v11, 31, v10
	v_lshlrev_b64 v[10:11], 13, v[10:11]
	v_lshl_add_u64 v[72:73], v[8:9], 0, v[10:11]
	v_or_b32_e32 v10, s7, v20
	v_ashrrev_i32_e32 v11, 31, v10
	v_lshlrev_b64 v[10:11], 13, v[10:11]
	v_lshl_add_u64 v[74:75], v[8:9], 0, v[10:11]
	global_load_dword v59, v[60:61], off nt
	global_load_dword v76, v[62:63], off nt
	global_load_dword v77, v[64:65], off nt
	global_load_dword v78, v[66:67], off nt
	global_load_dword v2, v[68:69], off nt
	global_load_dword v10, v[70:71], off nt
	global_load_dword v11, v[72:73], off nt
	global_load_dword v58, v[74:75], off nt
	s_waitcnt vmcnt(6)
	ds_write2_b32 v50, v59, v76 offset1:66
	s_waitcnt vmcnt(4)
	ds_write2_b32 v50, v77, v78 offset0:132 offset1:198

; #define LAS __attribute__((address_space(3)))
; __device__ __forceinline__ void wt_item(const float* __restrict__ W, int ldw, int K, int src_c0, bf16_t* __restrict__ WT, int dst_r0, int k0, LAS float* scr, int lane, int Ndst) {
; #pragma unroll 32
;     for (int i = 0; i < 32; ++i) { const int kk = 2 * i + (lane >> 5); scr[kk * 33 + (lane & 31)] = (src_c0 >= 0) ? W[(size_t)(k0 + kk) * ldw + src_c0 + (lane & 31)] : 0.f; }
.LBB0_122:
	v_mov_b32_e32 v2, 0
	s_andn2_b64 vcc, exec, s[0:1]
	v_mov_b32_e32 v10, 0
	v_mov_b32_e32 v11, 0
	v_mov_b32_e32 v58, 0
	s_cbranch_vccnz .LBB0_124
	v_or_b32_e32 v10, s7, v21
	v_ashrrev_i32_e32 v11, 31, v10
	v_lshlrev_b64 v[10:11], 13, v[10:11]
	v_lshl_add_u64 v[60:61], v[8:9], 0, v[10:11]
	v_or_b32_e32 v10, s7, v22
	v_ashrrev_i32_e32 v11, 31, v10
	v_lshlrev_b64 v[10:11], 13, v[10:11]
	v_lshl_add_u64 v[62:63], v[8:9], 0, v[10:11]
	v_or_b32_e32 v10, s7, v23
	v_ashrrev_i32_e32 v11, 31, v10
	v_lshlrev_b64 v[10:11], 13, v[10:11]
	v_lshl_add_u64 v[64:65], v[8:9], 0, v[10:11]
	v_or_b32_e32 v10, s7, v24
	v_ashrrev_i32_e32 v11, 31, v10
	v_lshlrev_b64 v[10:11], 13, v[10:11]
	v_lshl_add_u64 v[66:67], v[8:9], 0, v[10:11]
	v_or_b32_e32 v10, s7, v25
	v_ashrrev_i32_e32 v11, 31, v10
	v_lshlrev_b64 v[10:11], 13, v[10:11]
	v_lshl_add_u64 v[68:69], v[8:9], 0, v[10:11]
	v_or_b32_e32 v10, s7, v26
	v_ashrrev_i32_e32 v11, 31, v10
	v_lshlrev_b64 v[10:11], 13, v[10:11]
	v_lshl_add_u64 v[70:71], v[8:9], 0, v[10:11]
	v_or_b32_e32 v10, s7, v27
	v_ashrrev_i32_e32 v11, 31, v10
	v_lshlrev_b64 v[10:11], 13, v[10:11]
	v_lshl_add_u64 v[72:73], v[8:9], 0, v[10:11]
	v_or_b32_e32 v10, s7, v28
	v_ashrrev_i32_e32 v11, 31, v10
	v_lshlrev_b64 v[10:11], 13, v[10:11]
	v_lshl_add_u64 v[74:75], v[8:9], 0, v[10:11]
	global_load_dword v59, v[60:61], off nt
	global_load_dword v76, v[62:63], off nt
	global_load_dword v77, v[64:65], off nt
	global_load_dword v78, v[66:67], off nt
	global_load_dword v2, v[68:69], off nt
	global_load_dword v10, v[70:71], off nt
	global_load_dword v11, v[72:73], off nt
	global_load_dword v58, v[74:75], off nt
	s_waitcnt vmcnt(6)
	ds_write2_b32 v52, v59, v76 offset1:66
	s_waitcnt vmcnt(4)
	ds_write2_b32 v52, v77, v78 offset0:132 offset1:198

; #define LAS __attribute__((address_space(3)))
; __device__ __forceinline__ void wt_item(const float* __restrict__ W, int ldw, int K, int src_c0, bf16_t* __restrict__ WT, int dst_r0, int k0, LAS float* scr, int lane, int Ndst) {
; #pragma unroll 32
;     for (int i = 0; i < 32; ++i) { const int kk = 2 * i + (lane >> 5); scr[kk * 33 + (lane & 31)] = (src_c0 >= 0) ? W[(size_t)(k0 + kk) * ldw + src_c0 + (lane & 31)] : 0.f; }
.LBB0_126:
	v_mov_b32_e32 v2, 0
	s_andn2_b64 vcc, exec, s[0:1]
	v_mov_b32_e32 v10, 0
	v_mov_b32_e32 v11, 0
	v_mov_b32_e32 v58, 0
	s_cbranch_vccnz .LBB0_128
	v_or_b32_e32 v10, s7, v29
	v_ashrrev_i32_e32 v11, 31, v10
	v_lshlrev_b64 v[10:11], 13, v[10:11]
	v_lshl_add_u64 v[60:61], v[8:9], 0, v[10:11]
	v_or_b32_e32 v10, s7, v30
	v_ashrrev_i32_e32 v11, 31, v10
	v_lshlrev_b64 v[10:11], 13, v[10:11]
	v_lshl_add_u64 v[62:63], v[8:9], 0, v[10:11]
	v_or_b32_e32 v10, s7, v31
	v_ashrrev_i32_e32 v11, 31, v10
	v_lshlrev_b64 v[10:11], 13, v[10:11]
	v_lshl_add_u64 v[64:65], v[8:9], 0, v[10:11]
	v_or_b32_e32 v10, s7, v32
	v_ashrrev_i32_e32 v11, 31, v10
	v_lshlrev_b64 v[10:11], 13, v[10:11]
	v_lshl_add_u64 v[66:67], v[8:9], 0, v[10:11]
	v_or_b32_e32 v10, s7, v33
	v_ashrrev_i32_e32 v11, 31, v10
	v_lshlrev_b64 v[10:11], 13, v[10:11]
	v_lshl_add_u64 v[68:69], v[8:9], 0, v[10:11]
	v_or_b32_e32 v10, s7, v34
	v_ashrrev_i32_e32 v11, 31, v10
	v_lshlrev_b64 v[10:11], 13, v[10:11]
	v_lshl_add_u64 v[70:71], v[8:9], 0, v[10:11]
	v_or_b32_e32 v10, s7, v35
	v_ashrrev_i32_e32 v11, 31, v10
	v_lshlrev_b64 v[10:11], 13, v[10:11]
	v_lshl_add_u64 v[72:73], v[8:9], 0, v[10:11]
	v_or_b32_e32 v10, s7, v36
	v_ashrrev_i32_e32 v11, 31, v10
	v_lshlrev_b64 v[10:11], 13, v[10:11]
	v_lshl_add_u64 v[74:75], v[8:9], 0, v[10:11]
	global_load_dword v59, v[60:61], off nt
	global_load_dword v76, v[62:63], off nt
	global_load_dword v77, v[64:65], off nt
	global_load_dword v78, v[66:67], off nt
	global_load_dword v2, v[68:69], off nt
	global_load_dword v10, v[70:71], off nt
	global_load_dword v11, v[72:73], off nt
	global_load_dword v58, v[74:75], off nt
	s_waitcnt vmcnt(6)
	ds_write2_b32 v54, v59, v76 offset1:66
	s_waitcnt vmcnt(4)
	ds_write2_b32 v54, v77, v78 offset0:132 offset1:198

; #define LAS __attribute__((address_space(3)))
; __device__ __forceinline__ void wt_item(const float* __restrict__ W, int ldw, int K, int src_c0, bf16_t* __restrict__ WT, int dst_r0, int k0, LAS float* scr, int lane, int Ndst) {
; #pragma unroll 32
;     for (int i = 0; i < 32; ++i) { const int kk = 2 * i + (lane >> 5); scr[kk * 33 + (lane & 31)] = (src_c0 >= 0) ? W[(size_t)(k0 + kk) * ldw + src_c0 + (lane & 31)] : 0.f; }
.LBB0_130:
	v_mov_b32_e32 v2, 0
	s_andn2_b64 vcc, exec, s[0:1]
	v_mov_b32_e32 v10, 0
	v_mov_b32_e32 v11, 0
	v_mov_b32_e32 v58, 0
	s_cbranch_vccnz .LBB0_115
	v_or_b32_e32 v10, s7, v37
	v_ashrrev_i32_e32 v11, 31, v10
	v_lshlrev_b64 v[10:11], 13, v[10:11]
	v_lshl_add_u64 v[60:61], v[8:9], 0, v[10:11]
	v_or_b32_e32 v10, s7, v38
	v_ashrrev_i32_e32 v11, 31, v10
	v_lshlrev_b64 v[10:11], 13, v[10:11]
	v_lshl_add_u64 v[62:63], v[8:9], 0, v[10:11]
	v_or_b32_e32 v10, s7, v39
	v_ashrrev_i32_e32 v11, 31, v10
	v_lshlrev_b64 v[10:11], 13, v[10:11]
	v_lshl_add_u64 v[64:65], v[8:9], 0, v[10:11]
	v_or_b32_e32 v10, s7, v40
	v_ashrrev_i32_e32 v11, 31, v10
	v_lshlrev_b64 v[10:11], 13, v[10:11]
	v_lshl_add_u64 v[66:67], v[8:9], 0, v[10:11]
	v_or_b32_e32 v10, s7, v41
	v_ashrrev_i32_e32 v11, 31, v10
	v_lshlrev_b64 v[10:11], 13, v[10:11]
	v_lshl_add_u64 v[68:69], v[8:9], 0, v[10:11]
	v_or_b32_e32 v10, s7, v42
	v_ashrrev_i32_e32 v11, 31, v10
	v_lshlrev_b64 v[10:11], 13, v[10:11]
	v_lshl_add_u64 v[70:71], v[8:9], 0, v[10:11]
	v_or_b32_e32 v10, s7, v43
	v_ashrrev_i32_e32 v11, 31, v10
	v_lshlrev_b64 v[10:11], 13, v[10:11]
	v_lshl_add_u64 v[72:73], v[8:9], 0, v[10:11]
	v_or_b32_e32 v10, s7, v44
	v_ashrrev_i32_e32 v11, 31, v10
	v_lshlrev_b64 v[10:11], 13, v[10:11]
	v_lshl_add_u64 v[8:9], v[8:9], 0, v[10:11]
	global_load_dword v59, v[60:61], off nt
	global_load_dword v74, v[62:63], off nt
	global_load_dword v75, v[64:65], off nt
	global_load_dword v76, v[66:67], off nt
	global_load_dword v2, v[68:69], off nt
	global_load_dword v10, v[70:71], off nt
	global_load_dword v11, v[72:73], off nt
	global_load_dword v58, v[8:9], off nt
	s_waitcnt vmcnt(6)
	ds_write2_b32 v56, v59, v74 offset1:66
	s_waitcnt vmcnt(4)
	ds_write2_b32 v56, v75, v76 offset0:132 offset1:198
	s_branch .LBB0_115

; __device__ __forceinline__ float bf2f(unsigned h) { return __uint_as_float(h << 16); }
; __device__ __forceinline__ unsigned pk2(float lo, float hi) { return f2bf(lo) | (f2bf(hi) << 16); }
; __device__ __forceinline__ void mla_mid(const bf16_t* __restrict__ wino, const float* __restrict__ gq, const float* __restrict__ gkv, const float* __restrict__ cs_tab, const float* __restrict__ sn_tab, ...
;     ...
;     for (int m0 = 4 * gw; m0 < M_TOK; m0 += 4 * NGW) {
;         v4u v[4][2]; unsigned w[4]; float cc[4], ss[4];
; #pragma unroll
;         for (int rr = 0; rr < 4; ++rr) { const bf16_t* row = wino + (size_t)(m0 + rr) * 256; constexpr size_t TS = (size_t)M_TOK * 256;
;             v[rr][0] = *(const v4u*)(row + (size_t)(lane >> 5) * TS + (lane & 31) * 8); v[rr][1] = *(const v4u*)(row + (size_t)(2 + (lane >> 5)) * TS + (lane & 31) * 8);
;             w[rr] = *(const unsigned*)(row + 12 * TS + 2 * (lane & 31));
;             const int pos = (m0 + rr) & (SEQ - 1); cc[rr] = cs_tab[pos * 32 + (lane & 31)]; ss[rr] = sn_tab[pos * 32 + (lane & 31)]; }
; #pragma unroll
;         for (int rr = 0; rr < 4; ++rr) { const int m = m0 + rr;
; #pragma unroll
;             for (int part = 0; part < 2; ++part) {
;                 float f[8]; float s = 0.f;
; #pragma unroll
;                 for (int e = 0; e < 4; ++e) { f[2 * e] = bf2f(v[rr][part][e] & 0xffffu); f[2 * e + 1] = bf2f(v[rr][part][e] >> 16); s += f[2 * e] * f[2 * e] + f[2 * e + 1] * f[2 * e + 1]; }
;                 const float rstd = 1.0f / sqrtf(wave_sum(s) * (1.f / LORA) + RMS_EPS);
;                 const f32x4 g0 = part == 0 ? gq0 : gk0, g1 = part == 0 ? gq1 : gk1;
;                 v4u o; o.x = pk2(f[0] * rstd * g0[0], f[1] * rstd * g0[1]); o.y = pk2(f[2] * rstd * g0[2], f[3] * rstd * g0[3]);
;                 o.z = pk2(f[4] * rstd * g1[0], f[5] * rstd * g1[1]); o.w = pk2(f[6] * rstd * g1[2], f[7] * rstd * g1[3]);
;                 *(v4u*)((part == 0 ? cqn : ckvn) + ((size_t)(lane >> 3) * M_TOK + m) * 64 + (lane & 7) * 8) = o;
.LBB0_212:
	v_lshl_add_u64 v[16:17], v[4:5], 0, s[46:47]
	v_add_co_u32_e32 v18, vcc, 0x8800000, v16
	s_add_i32 s0, s8, 32
	s_nop 0
	v_addc_co_u32_e32 v19, vcc, 0, v17, vcc
	global_load_dwordx4 v[72:75], v[18:19], off nt
	v_add_co_u32_e32 v16, vcc, 0x9800000, v16
	s_and_b32 s0, s0, 0x3ffa0
	s_nop 0
	v_addc_co_u32_e32 v17, vcc, 0, v17, vcc
	global_load_dwordx4 v[40:43], v[16:17], off nt
	v_or_b32_e32 v20, s0, v1
	s_add_i32 s0, s8, 64
	v_lshlrev_b32_e32 v20, 2, v20
	s_and_b32 s0, s0, 0x3ffc0
	v_lshl_add_u64 v[70:71], v[52:53], 0, s[46:47]
	global_load_dwordx4 v[36:39], v[18:19], off offset:512 nt
	global_load_dwordx4 v[32:35], v[16:17], off offset:512 nt
	global_load_dword v61, v[70:71], off offset:-512
	global_load_dword v66, v20, s[34:35]
	global_load_dword v68, v20, s[86:87]
	global_load_dwordx4 v[28:31], v[18:19], off offset:1024 nt
	global_load_dwordx4 v[24:27], v[16:17], off offset:1024 nt
	global_load_dword v57, v[70:71], off
	v_or_b32_e32 v20, s0, v1
	v_lshlrev_b32_e32 v20, 2, v20
	s_add_i32 s0, s8, 0x60
	global_load_dword v60, v20, s[34:35]
	global_load_dword v62, v20, s[86:87]
	s_nop 0
	global_load_dwordx4 v[20:23], v[18:19], off offset:1536 nt
	s_nop 0
	global_load_dwordx4 v[16:19], v[16:17], off offset:1536 nt
	s_nop 0
	global_load_dword v55, v[70:71], off offset:512
	s_and_b32 s0, s0, 0x3ffe0
	s_waitcnt vmcnt(24)
	v_or_b32_e32 v54, s0, v1
	s_waitcnt vmcnt(23)
	v_lshlrev_b32_e32 v56, 2, v54
	global_load_dword v54, v56, s[34:35]
	s_nop 0
	global_load_dword v56, v56, s[86:87]
	s_waitcnt vmcnt(16)
	v_lshlrev_b32_e32 v59, 16, v73
	v_lshlrev_b32_e32 v58, 16, v72
	v_pk_mul_f32 v[64:65], v[58:59], v[58:59]
	v_and_b32_e32 v73, 0xffff0000, v73
	v_and_b32_e32 v72, 0xffff0000, v72
	v_lshlrev_b32_e32 v77, 16, v75
	v_lshlrev_b32_e32 v76, 16, v74
	v_pk_fma_f32 v[64:65], v[72:73], v[72:73], v[64:65]
	v_pk_mul_f32 v[78:79], v[76:77], v[76:77]
	v_and_b32_e32 v75, 0xffff0000, v75
	v_and_b32_e32 v74, 0xffff0000, v74
	v_pk_fma_f32 v[78:79], v[74:75], v[74:75], v[78:79]
	v_add_f32_e32 v63, v64, v65
	v_add_f32_e32 v63, v78, v63
	v_add_f32_e32 v63, v79, v63
	s_nop 1
	v_add_f32_dpp v63, v63, v63 quad_perm:[1,0,3,2] row_mask:0xf bank_mask:0xf bound_ctrl:1
	s_nop 1
	v_add_f32_dpp v63, v63, v63 quad_perm:[2,3,0,1] row_mask:0xf bank_mask:0xf bound_ctrl:1
	s_nop 1
	v_add_f32_dpp v63, v63, v63 row_half_mirror row_mask:0xf bank_mask:0xf bound_ctrl:1
	s_nop 1
	v_add_f32_dpp v63, v63, v63 row_mirror row_mask:0xf bank_mask:0xf bound_ctrl:1
	v_mov_b32_e32 v64, v63
	s_nop 1
	v_permlane16_swap_b32_e32 v63, v64
	v_add_f32_e32 v63, v63, v64
	v_mov_b32_e32 v64, v63
	s_nop 1
	v_permlane32_swap_b32_e32 v63, v64
	v_add_f32_e32 v63, v63, v64
	v_fmamk_f32 v63, v63, 0x3b000000, v218
	v_cmp_gt_f32_e32 vcc, s30, v63
	v_mul_f32_e32 v64, 0x4f800000, v63
	s_nop 0
	v_cndmask_b32_e32 v63, v63, v64, vcc
	v_sqrt_f32_e32 v64, v63
	s_nop 0
	v_add_u32_e32 v65, -1, v64
	v_fma_f32 v67, -v65, v64, v63
	v_cmp_ge_f32_e64 s[42:43], 0, v67
	v_add_u32_e32 v67, 1, v64
	s_nop 0
	v_cndmask_b32_e64 v65, v64, v65, s[42:43]
	v_fma_f32 v64, -v67, v64, v63
	v_cmp_lt_f32_e64 s[42:43], 0, v64
	s_nop 1
	v_cndmask_b32_e64 v64, v65, v67, s[42:43]
	v_mul_f32_e32 v65, 0x37800000, v64
	v_cndmask_b32_e32 v64, v64, v65, vcc
	v_cmp_class_f32_e32 vcc, v63, v215
	s_nop 1
	v_cndmask_b32_e32 v63, v64, v63, vcc
	v_div_scale_f32 v64, s[0:1], v63, v63, 1.0
	v_rcp_f32_e32 v65, v64
	s_mov_b32 s0, 0x1d000000
	v_fma_f32 v67, -v64, v65, 1.0
	v_fmac_f32_e32 v65, v67, v65
	v_div_scale_f32 v67, vcc, 1.0, v63, 1.0
	v_mul_f32_e32 v69, v67, v65
	v_fma_f32 v78, -v64, v69, v67
	v_fmac_f32_e32 v69, v78, v65
	v_fma_f32 v64, -v64, v69, v67
	v_div_fmas_f32 v64, v64, v65, v69
	v_div_fixup_f32 v64, v64, v63, 1.0
	v_pk_mul_f32 v[58:59], v[64:65], v[58:59] op_sel_hi:[0,1]
	v_pk_mul_f32 v[72:73], v[64:65], v[72:73] op_sel_hi:[0,1]
	v_pk_mul_f32 v[76:77], v[64:65], v[76:77] op_sel_hi:[0,1]
	v_pk_mul_f32 v[64:65], v[64:65], v[74:75] op_sel_hi:[0,1]
	v_pk_mul_f32 v[64:65], v[46:47], v[64:65]
	v_pk_mul_f32 v[58:59], v[14:15], v[58:59]
	v_pk_mul_f32 v[72:73], v[44:45], v[72:73]
	v_bfe_u32 v63, v65, 16, 1
	v_bfe_u32 v67, v64, 16, 1
	v_pk_mul_f32 v[76:77], v[10:11], v[76:77]
	v_bfe_u32 v69, v73, 16, 1
	v_add3_u32 v64, v64, v67, s63
	v_add3_u32 v63, v65, v63, s63
	v_bfe_u32 v65, v58, 16, 1
	v_bfe_u32 v67, v59, 16, 1
	v_bfe_u32 v74, v72, 16, 1
	v_add3_u32 v69, v73, v69, s63
	v_bfe_u32 v73, v76, 16, 1
	v_add3_u32 v59, v59, v67, s63
	v_add3_u32 v58, v58, v65, s63
	v_add3_u32 v72, v72, v74, s63
	v_bfe_u32 v74, v77, 16, 1
	v_add3_u32 v73, v76, v73, s63
	v_lshrrev_b32_e32 v58, 16, v58
	v_lshrrev_b32_e32 v59, 16, v59
	v_add3_u32 v74, v77, v74, s63
	v_lshrrev_b32_e32 v65, 16, v73
	v_and_or_b32 v73, v69, s60, v59
	v_and_or_b32 v72, v72, s60, v58
	v_lshl_add_u64 v[58:59], v[48:49], 0, s[46:47]
	v_lshrrev_b32_e32 v67, 16, v74
	v_and_or_b32 v74, v64, s60, v65
	v_add_co_u32_e32 v64, vcc, s0, v58
	v_and_or_b32 v75, v63, s60, v67
	s_nop 0
	v_addc_co_u32_e32 v65, vcc, 0, v59, vcc
	global_store_dwordx4 v[64:65], v[72:75], off sc0 sc1
	s_waitcnt vmcnt(16)
; __device__ __forceinline__ float bf2f(unsigned h) { return __uint_as_float(h << 16); }
; __device__ __forceinline__ unsigned pk2(float lo, float hi) { return f2bf(lo) | (f2bf(hi) << 16); }
; __device__ __forceinline__ void mla_mid(const bf16_t* __restrict__ wino, const float* __restrict__ gq, const float* __restrict__ gkv, const float* __restrict__ cs_tab, const float* __restrict__ sn_tab, ...
;     ...
;         for (int rr = 0; rr < 4; ++rr) { const int m = m0 + rr;
; #pragma unroll
;             for (int part = 0; part < 2; ++part) {
;                 float f[8]; float s = 0.f;
; #pragma unroll
;                 for (int e = 0; e < 4; ++e) { f[2 * e] = bf2f(v[rr][part][e] & 0xffffu); f[2 * e + 1] = bf2f(v[rr][part][e] >> 16); s += f[2 * e] * f[2 * e] + f[2 * e + 1] * f[2 * e + 1]; }
;                 const float rstd = 1.0f / sqrtf(wave_sum(s) * (1.f / LORA) + RMS_EPS);
;                 const f32x4 g0 = part == 0 ? gq0 : gk0, g1 = part == 0 ? gq1 : gk1;
;                 v4u o; o.x = pk2(f[0] * rstd * g0[0], f[1] * rstd * g0[1]); o.y = pk2(f[2] * rstd * g0[2], f[3] * rstd * g0[3]);
;                 o.z = pk2(f[4] * rstd * g1[0], f[5] * rstd * g1[1]); o.w = pk2(f[6] * rstd * g1[2], f[7] * rstd * g1[3]);
;                 *(v4u*)((part == 0 ? cqn : ckvn) + ((size_t)(lane >> 3) * M_TOK + m) * 64 + (lane & 7) * 8) = o;
;             }
;             if (lane < 32) { const float x1 = bf2f(w[rr] & 0xffffu), x2 = bf2f(w[rr] >> 16);
;                 *(unsigned*)(kr + (size_t)m * 64 + 2 * lane) = pk2(x1 * cc[rr] - x2 * ss[rr], x1 * ss[rr] + x2 * cc[rr]); }
	v_lshlrev_b32_e32 v77, 16, v43
	v_lshlrev_b32_e32 v76, 16, v42
	v_lshlrev_b32_e32 v73, 16, v41
	v_lshlrev_b32_e32 v72, 16, v40
	v_pk_mul_f32 v[74:75], v[72:73], v[72:73]
	v_and_b32_e32 v41, 0xffff0000, v41
	v_and_b32_e32 v40, 0xffff0000, v40
	v_pk_fma_f32 v[74:75], v[40:41], v[40:41], v[74:75]
	v_pk_mul_f32 v[78:79], v[76:77], v[76:77]
	v_and_b32_e32 v43, 0xffff0000, v43
	v_and_b32_e32 v42, 0xffff0000, v42
	v_pk_fma_f32 v[78:79], v[42:43], v[42:43], v[78:79]
	v_add_f32_e32 v63, v74, v75
	v_add_f32_e32 v63, v78, v63
	v_add_f32_e32 v63, v79, v63
	s_nop 1
	v_add_f32_dpp v63, v63, v63 quad_perm:[1,0,3,2] row_mask:0xf bank_mask:0xf bound_ctrl:1
	s_nop 1
	v_add_f32_dpp v63, v63, v63 quad_perm:[2,3,0,1] row_mask:0xf bank_mask:0xf bound_ctrl:1
	s_nop 1
	v_add_f32_dpp v63, v63, v63 row_half_mirror row_mask:0xf bank_mask:0xf bound_ctrl:1
	s_nop 1
	v_add_f32_dpp v63, v63, v63 row_mirror row_mask:0xf bank_mask:0xf bound_ctrl:1
	v_mov_b32_e32 v67, v63
	s_nop 1
	v_permlane16_swap_b32_e32 v63, v67
	v_add_f32_e32 v63, v63, v67
	v_mov_b32_e32 v67, v63
	s_nop 1
	v_permlane32_swap_b32_e32 v63, v67
	v_add_f32_e32 v63, v63, v67
	v_fmamk_f32 v63, v63, 0x3b000000, v218
	v_cmp_gt_f32_e32 vcc, s30, v63
	v_mul_f32_e32 v67, 0x4f800000, v63
	s_nop 0
	v_cndmask_b32_e32 v63, v63, v67, vcc
	v_sqrt_f32_e32 v67, v63
	s_nop 0
	v_add_u32_e32 v69, -1, v67
	v_fma_f32 v74, -v69, v67, v63
	v_cmp_ge_f32_e64 s[42:43], 0, v74
	v_add_u32_e32 v74, 1, v67
	s_nop 0
	v_cndmask_b32_e64 v69, v67, v69, s[42:43]
	v_fma_f32 v67, -v74, v67, v63
	v_cmp_lt_f32_e64 s[42:43], 0, v67
	s_nop 1
	v_cndmask_b32_e64 v67, v69, v74, s[42:43]
	v_mul_f32_e32 v69, 0x37800000, v67
	v_cndmask_b32_e32 v67, v67, v69, vcc
	v_cmp_class_f32_e32 vcc, v63, v215
	s_nop 1
	v_cndmask_b32_e32 v63, v67, v63, vcc
	v_div_scale_f32 v67, s[0:1], v63, v63, 1.0
	v_rcp_f32_e32 v69, v67
	s_nop 0
	v_fma_f32 v74, -v67, v69, 1.0
	v_fmac_f32_e32 v69, v74, v69
	v_div_scale_f32 v74, vcc, 1.0, v63, 1.0
	v_mul_f32_e32 v75, v74, v69
	v_fma_f32 v78, -v67, v75, v74
	v_fmac_f32_e32 v75, v78, v69
	v_fma_f32 v67, -v67, v75, v74
	v_div_fmas_f32 v67, v67, v69, v75
	v_div_fixup_f32 v74, v67, v63, 1.0
	v_pk_mul_f32 v[40:41], v[74:75], v[40:41] op_sel_hi:[0,1]
	v_pk_mul_f32 v[40:41], v[12:13], v[40:41]
	v_pk_mul_f32 v[76:77], v[74:75], v[76:77] op_sel_hi:[0,1]
	v_pk_mul_f32 v[42:43], v[74:75], v[42:43] op_sel_hi:[0,1]
	v_pk_mul_f32 v[72:73], v[74:75], v[72:73] op_sel_hi:[0,1]
	v_pk_mul_f32 v[76:77], v[2:3], v[76:77]
	v_pk_mul_f32 v[42:43], v[8:9], v[42:43]
	v_bfe_u32 v74, v40, 16, 1
	v_pk_mul_f32 v[72:73], v[6:7], v[72:73]
	v_bfe_u32 v63, v43, 16, 1
	v_bfe_u32 v67, v42, 16, 1
	v_bfe_u32 v69, v41, 16, 1
	v_add3_u32 v40, v40, v74, s63
	v_bfe_u32 v74, v77, 16, 1
	v_add3_u32 v41, v41, v69, s63
	v_add3_u32 v42, v42, v67, s63
	v_add3_u32 v43, v43, v63, s63
	v_bfe_u32 v63, v72, 16, 1
	v_bfe_u32 v67, v73, 16, 1
	v_bfe_u32 v69, v76, 16, 1
	v_add3_u32 v74, v77, v74, s63
	v_add3_u32 v69, v76, v69, s63
	v_add3_u32 v67, v73, v67, s63
	v_add3_u32 v63, v72, v63, s63
	v_lshrrev_b32_e32 v72, 16, v74
	v_lshrrev_b32_e32 v63, 16, v63
	v_lshrrev_b32_e32 v67, 16, v67
	v_lshrrev_b32_e32 v69, 16, v69
	v_and_or_b32 v43, v43, s60, v72
	v_add_co_u32_e32 v72, vcc, 0x1e000000, v58
	v_and_or_b32 v42, v42, s60, v69
	v_and_or_b32 v41, v41, s60, v67
	v_and_or_b32 v40, v40, s60, v63
	v_addc_co_u32_e32 v73, vcc, 0, v59, vcc
	global_store_dwordx4 v[72:73], v[40:43], off sc0 sc1
	s_nop 1
	v_lshl_add_u64 v[40:41], v[50:51], 0, s[46:47]
	s_and_saveexec_b64 s[6:7], s[40:41]
	s_cbranch_execz .LBB0_214
	s_and_b32 s0, s8, 0x3ff80
	global_load_dword v43, v[70:71], off offset:-1024
	v_or_b32_e32 v42, s0, v1
	v_lshlrev_b32_e32 v63, 2, v42
	global_load_dword v42, v63, s[86:87]
	global_load_dword v70, v63, s[34:35]
	s_waitcnt vmcnt(2)
	v_lshlrev_b32_e32 v73, 16, v43
	v_and_b32_e32 v72, 0xffff0000, v43
	s_waitcnt vmcnt(1)
	v_pk_mul_f32 v[42:43], v[42:43], v[72:73] op_sel:[0,1] op_sel_hi:[0,0]
	s_waitcnt vmcnt(0)
	v_pk_fma_f32 v[74:75], v[70:71], v[72:73], v[42:43]
	v_pk_fma_f32 v[42:43], v[70:71], v[72:73], v[42:43] op_sel_hi:[0,1,1] neg_lo:[0,0,1] neg_hi:[0,0,1]
	v_and_b32_sdwa v42, v43, v217 dst_sel:DWORD dst_unused:UNUSED_PAD src0_sel:WORD_1 src1_sel:DWORD
	v_and_b32_sdwa v63, v74, v217 dst_sel:DWORD dst_unused:UNUSED_PAD src0_sel:WORD_1 src1_sel:DWORD
	v_add3_u32 v42, v43, v42, s63
	v_add3_u32 v63, v74, v63, s63
	v_lshrrev_b32_e32 v42, 16, v42
	v_and_or_b32 v42, v63, s60, v42
	global_store_dword v[40:41], v42, off offset:-256

; #define LAS __attribute__((address_space(3)))
; __device__ __forceinline__ void wt_item(const float* __restrict__ W, int ldw, int K, int src_c0, bf16_t* __restrict__ WT, int dst_r0, int k0, LAS float* scr, int lane, int Ndst) {
; #pragma unroll 32
;     for (int i = 0; i < 32; ++i) { const int kk = 2 * i + (lane >> 5); scr[kk * 33 + (lane & 31)] = (src_c0 >= 0) ? W[(size_t)(k0 + kk) * ldw + src_c0 + (lane & 31)] : 0.f; }
; __device__ __forceinline__ void conv_generic(const float* W, int ldw, int K, int Ndst, bool win_map, bf16_t* WT, LAS float* scr, int gw, int NGW, int lane) {
;     const int nblk = Ndst / 32, items = (K / 64) * nblk;
;     for (int it = gw; it < items; it += NGW) { const int kb = it / nblk, nb = it % nblk; int src = nb * 32;
;         if (win_map) src = nb < 32 ? nb * 32 : nb < 96 ? 1088 + (nb - 32) * 32 : nb < 98 ? 1024 + (nb - 96) * 32 : -1;
;         wt_item(W, ldw, K, src, WT, nb * 32, kb * 64, scr, lane, Ndst); }
.LBB0_417:
	s_lshl_b32 s23, s22, 6
	v_lshl_add_u64 v[18:19], s[10:11], 2, v[14:15]
	v_mov_b32_e32 v11, 0
	s_andn2_b64 vcc, exec, s[0:1]
	v_mov_b32_e32 v13, 0
	v_mov_b32_e32 v51, 0
	v_mov_b32_e32 v52, 0
	s_cbranch_vccnz .LBB0_419
	v_or_b32_e32 v11, s23, v1
	s_ashr_i32 s0, s23, 31
	v_mul_lo_u32 v13, s43, v11
	s_mul_i32 s5, s42, s0
	v_mad_u64_u32 v[52:53], s[0:1], s42, v11, 0
	v_add3_u32 v53, v53, s5, v13
	v_lshl_add_u64 v[52:53], v[52:53], 2, v[18:19]
	v_or_b32_e32 v13, s23, v3
	global_load_dword v11, v[52:53], off nt
	v_mul_lo_u32 v51, s43, v13
	v_mad_u64_u32 v[52:53], s[0:1], s42, v13, 0
	v_add3_u32 v53, v53, s5, v51
	v_lshl_add_u64 v[52:53], v[52:53], 2, v[18:19]
	v_or_b32_e32 v51, s23, v5
	global_load_dword v13, v[52:53], off nt
	s_waitcnt vmcnt(0)
	v_mul_lo_u32 v54, s43, v51
	v_mad_u64_u32 v[52:53], s[0:1], s42, v51, 0
	v_add3_u32 v53, v53, s5, v54
	v_lshl_add_u64 v[52:53], v[52:53], 2, v[18:19]
	global_load_dword v51, v[52:53], off nt
	v_or_b32_e32 v52, s23, v7
	v_mul_lo_u32 v54, s43, v52
	v_mad_u64_u32 v[52:53], s[0:1], s42, v52, 0
	v_add3_u32 v53, v53, s5, v54
	v_lshl_add_u64 v[52:53], v[52:53], 2, v[18:19]
	global_load_dword v52, v[52:53], off nt
	ds_write2_b32 v49, v11, v13 offset1:66
	s_waitcnt vmcnt(0)
	ds_write2_b32 v49, v51, v52 offset0:132 offset1:198
	v_or_b32_e32 v11, s23, v9
	v_mul_lo_u32 v13, s43, v11
	v_mad_u64_u32 v[52:53], s[0:1], s42, v11, 0
	v_add3_u32 v53, v53, s5, v13
	v_lshl_add_u64 v[52:53], v[52:53], 2, v[18:19]
	v_or_b32_e32 v13, s23, v20
	global_load_dword v11, v[52:53], off nt
	v_mul_lo_u32 v51, s43, v13
	v_mad_u64_u32 v[52:53], s[0:1], s42, v13, 0
	v_add3_u32 v53, v53, s5, v51
	v_lshl_add_u64 v[52:53], v[52:53], 2, v[18:19]
	v_or_b32_e32 v51, s23, v21
	global_load_dword v13, v[52:53], off nt
	v_mul_lo_u32 v54, s43, v51
	v_mad_u64_u32 v[52:53], s[0:1], s42, v51, 0
	v_add3_u32 v53, v53, s5, v54
	v_lshl_add_u64 v[52:53], v[52:53], 2, v[18:19]
	global_load_dword v51, v[52:53], off nt
	v_or_b32_e32 v52, s23, v22
	v_mul_lo_u32 v54, s43, v52
	v_mad_u64_u32 v[52:53], s[0:1], s42, v52, 0
	v_add3_u32 v53, v53, s5, v54
	v_lshl_add_u64 v[52:53], v[52:53], 2, v[18:19]
	global_load_dword v52, v[52:53], off nt

; #define LAS __attribute__((address_space(3)))
; __device__ __forceinline__ void wt_item(const float* __restrict__ W, int ldw, int K, int src_c0, bf16_t* __restrict__ WT, int dst_r0, int k0, LAS float* scr, int lane, int Ndst) {
; #pragma unroll 32
;     for (int i = 0; i < 32; ++i) { const int kk = 2 * i + (lane >> 5); scr[kk * 33 + (lane & 31)] = (src_c0 >= 0) ? W[(size_t)(k0 + kk) * ldw + src_c0 + (lane & 31)] : 0.f; }
.LBB0_421:
	v_mov_b32_e32 v11, 0
	s_andn2_b64 vcc, exec, s[0:1]
	v_mov_b32_e32 v13, 0
	v_mov_b32_e32 v51, 0
	v_mov_b32_e32 v52, 0
	s_cbranch_vccnz .LBB0_423
	v_or_b32_e32 v11, s23, v23
	s_ashr_i32 s0, s23, 31
	v_mul_lo_u32 v13, s43, v11
	s_mul_i32 s5, s42, s0
	v_mad_u64_u32 v[52:53], s[0:1], s42, v11, 0
	v_add3_u32 v53, v53, s5, v13
	v_lshl_add_u64 v[52:53], v[52:53], 2, v[18:19]
	v_or_b32_e32 v13, s23, v24
	global_load_dword v11, v[52:53], off nt
	v_mul_lo_u32 v51, s43, v13
	v_mad_u64_u32 v[52:53], s[0:1], s42, v13, 0
	v_add3_u32 v53, v53, s5, v51
	v_lshl_add_u64 v[52:53], v[52:53], 2, v[18:19]
	v_or_b32_e32 v51, s23, v25
	global_load_dword v13, v[52:53], off nt
	v_mul_lo_u32 v54, s43, v51
	v_mad_u64_u32 v[52:53], s[0:1], s42, v51, 0
	v_add3_u32 v53, v53, s5, v54
	v_lshl_add_u64 v[52:53], v[52:53], 2, v[18:19]
	global_load_dword v51, v[52:53], off nt
	v_or_b32_e32 v52, s23, v26
	v_mul_lo_u32 v54, s43, v52
	v_mad_u64_u32 v[52:53], s[0:1], s42, v52, 0
	v_add3_u32 v53, v53, s5, v54
	v_lshl_add_u64 v[52:53], v[52:53], 2, v[18:19]
	global_load_dword v52, v[52:53], off nt
	s_waitcnt vmcnt(2)
	ds_write2_b32 v50, v11, v13 offset1:66
	s_waitcnt vmcnt(0)
	ds_write2_b32 v50, v51, v52 offset0:132 offset1:198
	v_or_b32_e32 v11, s23, v27
	v_mul_lo_u32 v13, s43, v11
	v_mad_u64_u32 v[52:53], s[0:1], s42, v11, 0
	v_add3_u32 v53, v53, s5, v13
	v_lshl_add_u64 v[52:53], v[52:53], 2, v[18:19]
	v_or_b32_e32 v13, s23, v28
	global_load_dword v11, v[52:53], off nt
	v_mul_lo_u32 v51, s43, v13
	v_mad_u64_u32 v[52:53], s[0:1], s42, v13, 0
	v_add3_u32 v53, v53, s5, v51
	v_lshl_add_u64 v[52:53], v[52:53], 2, v[18:19]
	v_or_b32_e32 v51, s23, v29
	global_load_dword v13, v[52:53], off nt
	v_mul_lo_u32 v54, s43, v51
	v_mad_u64_u32 v[52:53], s[0:1], s42, v51, 0
	v_add3_u32 v53, v53, s5, v54
	v_lshl_add_u64 v[52:53], v[52:53], 2, v[18:19]
	global_load_dword v51, v[52:53], off nt
	v_or_b32_e32 v52, s23, v30
	v_mul_lo_u32 v54, s43, v52
	v_mad_u64_u32 v[52:53], s[0:1], s42, v52, 0
	v_add3_u32 v53, v53, s5, v54
	v_lshl_add_u64 v[52:53], v[52:53], 2, v[18:19]
	global_load_dword v52, v[52:53], off nt

; #define LAS __attribute__((address_space(3)))
; __device__ __forceinline__ void wt_item(const float* __restrict__ W, int ldw, int K, int src_c0, bf16_t* __restrict__ WT, int dst_r0, int k0, LAS float* scr, int lane, int Ndst) {
; #pragma unroll 32
;     for (int i = 0; i < 32; ++i) { const int kk = 2 * i + (lane >> 5); scr[kk * 33 + (lane & 31)] = (src_c0 >= 0) ? W[(size_t)(k0 + kk) * ldw + src_c0 + (lane & 31)] : 0.f; }
.LBB0_425:
	v_mov_b32_e32 v11, 0
	s_andn2_b64 vcc, exec, s[0:1]
	v_mov_b32_e32 v51, 0
	v_mov_b32_e32 v52, 0
	v_mov_b32_e32 v53, 0
	s_cbranch_vccnz .LBB0_427
	v_or_b32_e32 v11, s23, v31
	s_ashr_i32 s0, s23, 31
	v_mul_lo_u32 v51, s43, v11
	s_mul_i32 s5, s42, s0
	v_mad_u64_u32 v[52:53], s[0:1], s42, v11, 0
	v_add3_u32 v53, v53, s5, v51
	v_lshl_add_u64 v[52:53], v[52:53], 2, v[18:19]
	v_or_b32_e32 v51, s23, v32
	global_load_dword v11, v[52:53], off nt
	v_mul_lo_u32 v54, s43, v51
	v_mad_u64_u32 v[52:53], s[0:1], s42, v51, 0
	v_add3_u32 v53, v53, s5, v54
	v_lshl_add_u64 v[52:53], v[52:53], 2, v[18:19]
	global_load_dword v51, v[52:53], off nt
	v_or_b32_e32 v52, s23, v33
	v_mul_lo_u32 v54, s43, v52
	v_mad_u64_u32 v[52:53], s[0:1], s42, v52, 0
	v_add3_u32 v53, v53, s5, v54
	v_lshl_add_u64 v[52:53], v[52:53], 2, v[18:19]
	global_load_dword v54, v[52:53], off nt
	v_or_b32_e32 v52, s23, v34
	v_mul_lo_u32 v55, s43, v52
	v_mad_u64_u32 v[52:53], s[0:1], s42, v52, 0
	v_add3_u32 v53, v53, s5, v55
	v_lshl_add_u64 v[52:53], v[52:53], 2, v[18:19]
	global_load_dword v52, v[52:53], off nt
	s_waitcnt vmcnt(2)
	ds_write2_b32 v13, v11, v51 offset0:16 offset1:82
	s_waitcnt vmcnt(0)
	ds_write2_b32 v13, v54, v52 offset0:148 offset1:214
	v_or_b32_e32 v11, s23, v35
	v_mul_lo_u32 v13, s43, v11
	v_mad_u64_u32 v[52:53], s[0:1], s42, v11, 0
	v_add3_u32 v53, v53, s5, v13
	v_lshl_add_u64 v[52:53], v[52:53], 2, v[18:19]
	v_or_b32_e32 v13, s23, v36
	global_load_dword v11, v[52:53], off nt
	v_mul_lo_u32 v51, s43, v13
	v_mad_u64_u32 v[52:53], s[0:1], s42, v13, 0
	v_add3_u32 v53, v53, s5, v51
	v_lshl_add_u64 v[52:53], v[52:53], 2, v[18:19]
	v_or_b32_e32 v13, s23, v37
	global_load_dword v51, v[52:53], off nt
	v_mul_lo_u32 v54, s43, v13
	v_mad_u64_u32 v[52:53], s[0:1], s42, v13, 0
	v_add3_u32 v53, v53, s5, v54
	v_lshl_add_u64 v[52:53], v[52:53], 2, v[18:19]
	v_or_b32_e32 v13, s23, v38
	global_load_dword v52, v[52:53], off nt
	v_mul_lo_u32 v53, s43, v13
	v_mad_u64_u32 v[54:55], s[0:1], s42, v13, 0
	v_add3_u32 v55, v55, s5, v53
	v_lshl_add_u64 v[54:55], v[54:55], 2, v[18:19]
	global_load_dword v53, v[54:55], off nt

; #define LAS __attribute__((address_space(3)))
; #define LDS_WAIT() asm volatile("s_waitcnt lgkmcnt(0)" ::: "memory")
; __device__ __forceinline__ void wt_item(const float* __restrict__ W, int ldw, int K, int src_c0, bf16_t* __restrict__ WT, int dst_r0, int k0, LAS float* scr, int lane, int Ndst) {
; #pragma unroll 32
;     for (int i = 0; i < 32; ++i) { const int kk = 2 * i + (lane >> 5); scr[kk * 33 + (lane & 31)] = (src_c0 >= 0) ? W[(size_t)(k0 + kk) * ldw + src_c0 + (lane & 31)] : 0.f; }
;     LDS_WAIT(); asm volatile("" ::: "memory");
.LBB0_429:
	v_mov_b32_e32 v11, 0
	s_andn2_b64 vcc, exec, s[0:1]
	v_mov_b32_e32 v51, 0
	v_mov_b32_e32 v52, 0
	v_mov_b32_e32 v53, 0
	s_cbranch_vccnz .LBB0_409
	v_or_b32_e32 v11, s23, v39
	s_ashr_i32 s0, s23, 31
	v_mul_lo_u32 v51, s43, v11
	s_mul_i32 s5, s42, s0
	v_mad_u64_u32 v[52:53], s[0:1], s42, v11, 0
	v_add3_u32 v53, v53, s5, v51
	v_lshl_add_u64 v[52:53], v[52:53], 2, v[18:19]
	v_or_b32_e32 v51, s23, v40
	global_load_dword v11, v[52:53], off nt
	v_mul_lo_u32 v54, s43, v51
	v_mad_u64_u32 v[52:53], s[0:1], s42, v51, 0
	v_add3_u32 v53, v53, s5, v54
	v_lshl_add_u64 v[52:53], v[52:53], 2, v[18:19]
	global_load_dword v51, v[52:53], off nt
	v_or_b32_e32 v52, s23, v41
	v_mul_lo_u32 v54, s43, v52
	v_mad_u64_u32 v[52:53], s[0:1], s42, v52, 0
	v_add3_u32 v53, v53, s5, v54
	v_lshl_add_u64 v[52:53], v[52:53], 2, v[18:19]
	global_load_dword v54, v[52:53], off nt
	v_or_b32_e32 v52, s23, v42
	v_mul_lo_u32 v55, s43, v52
	v_mad_u64_u32 v[52:53], s[0:1], s42, v52, 0
	v_add3_u32 v53, v53, s5, v55
	v_lshl_add_u64 v[52:53], v[52:53], 2, v[18:19]
	global_load_dword v52, v[52:53], off nt
	s_waitcnt vmcnt(2)
	ds_write2_b32 v13, v11, v51 offset0:32 offset1:98
	s_waitcnt vmcnt(0)
	ds_write2_b32 v13, v54, v52 offset0:164 offset1:230
	v_or_b32_e32 v11, s23, v43
	v_mul_lo_u32 v13, s43, v11
	v_mad_u64_u32 v[52:53], s[0:1], s42, v11, 0
	v_add3_u32 v53, v53, s5, v13
	v_lshl_add_u64 v[52:53], v[52:53], 2, v[18:19]
	v_or_b32_e32 v13, s23, v44
	global_load_dword v11, v[52:53], off nt
	v_mul_lo_u32 v51, s43, v13
	v_mad_u64_u32 v[52:53], s[0:1], s42, v13, 0
	v_add3_u32 v53, v53, s5, v51
	v_lshl_add_u64 v[52:53], v[52:53], 2, v[18:19]
	v_or_b32_e32 v13, s23, v45
	global_load_dword v51, v[52:53], off nt
	v_mul_lo_u32 v54, s43, v13
	v_mad_u64_u32 v[52:53], s[0:1], s42, v13, 0
	v_add3_u32 v53, v53, s5, v54
	v_lshl_add_u64 v[52:53], v[52:53], 2, v[18:19]
	v_or_b32_e32 v13, s23, v46
	global_load_dword v52, v[52:53], off nt
	v_mul_lo_u32 v53, s43, v13
	v_mad_u64_u32 v[54:55], s[0:1], s42, v13, 0
	v_add3_u32 v55, v55, s5, v53
	v_lshl_add_u64 v[18:19], v[54:55], 2, v[18:19]
	global_load_dword v53, v[18:19], off nt
	s_branch .LBB0_409
